# P3: one head per workgroup (spatial weights, bias, layer-norm gains stay in registers), v/u tiles prefetched two units ahead, triple-buffered LDS tile
# speedup vs baseline: 1.0152x; 1.0048x over previous
; #define tid (otid())
; #define wave (__builtin_amdgcn_readfirstlane((int)(threadIdx.x >> 6)))
; __global__ void __launch_bounds__(512, 2) mega_fwd(Args a) {
;     ...
;         const int r32 = lane & 31, hi = lane >> 5, iblk = wave >> 1, dblk = wave & 1;
;         const int jt = tid >> 2, qd = tid & 3;
;         u32x4 r0, r1; f32x4 lgv[4], lbv[4];
;         const int ustep = (G == 256) ? 1 : G;
;         const int jx = vcu & 31;
;         const int u0 = (G == 256) ? (256 * (vcu >> 5) + (jx < 16 ? 7 * jx : 112 + 9 * (jx - 16))) : vcu;
;         const int ucnt = (G == 256) ? (bx < 128 ? 7 : 9) : (vcu < 2048 ? (2047 - vcu) / G + 1 : 0);
;         if (ucnt > 0) { const bf16_t* vp = Z + ((size_t)(u0 >> 3) * 128 + jt) * NZ + 1024 + (u0 & 7) * 64 + 16 * qd; r0 = *(const u32x4*)vp; r1 = *(const u32x4*)(vp + 8);
; #pragma unroll
;             for (int e4 = 0; e4 < 4; ++e4) { lgv[e4] = *(const f32x4*)(KA->gm_ln_g + (u0 & 7) * 64 + 16 * qd + 4 * e4); lbv[e4] = *(const f32x4*)(KA->gm_ln_b + (u0 & 7) * 64 + 16 * qd + 4 * e4); } }
.LBB0_340:
	s_cmp_lt_i32 s18, 1
	s_cbranch_scc1 .LBB0_361
	s_load_dwordx2 s[8:9], s[6:7], 0xb8
	s_load_dwordx4 s[40:43], s[6:7], 0x58
	s_load_dwordx2 s[16:17], s[6:7], 0x70
	s_and_b64 s[4:5], s[4:5], exec
	s_cselect_b32 s19, 1, s28
	s_mov_b32 s38, 0xffff0000
	v_mov_b32_e32 v111, 0x358637bd
	v_and_b32_e32 v104, 3, v0
	v_lshrrev_b32_e32 v105, 2, v0
	v_and_b32_e32 v106, 31, v0
	v_bfe_u32 v107, v0, 5, 1
	s_lshr_b32 s4, s20, 7
	s_bfe_u32 s5, s20, 0x10006
	s_lshl_b32 s10, s4, 5
	v_or_b32_e32 v108, s10, v106
	v_mul_u32_u24_e32 v112, 0xc00, v105
	v_lshl_add_u32 v112, v104, 5, v112
	v_add_u32_e32 v112, 0x800, v112
	s_lshl_b32 s11, s5, 6
	s_add_u32 s11, s11, 0x400
	v_mul_u32_u24_e32 v113, 0xc00, v108
	v_lshl_add_u32 v113, v107, 3, v113
	v_add_u32_e32 v113, s11, v113
	v_lshlrev_b32_e32 v116, 11, v108
	v_lshl_add_u32 v116, v107, 3, v116
	v_add_u32_e32 v116, s11, v116
	v_lshlrev_b32_e32 v114, 8, v108
	v_lshl_add_u32 v114, v107, 4, v114
	v_lshlrev_b32_e32 v115, 2, v108
	v_mul_u32_u24_e32 v117, 0x1100, v104
	v_lshl_add_u32 v117, v105, 1, v117
	s_lshl_b32 s12, s5, 5
	v_or_b32_e32 v118, s12, v106
	v_mul_u32_u24_e32 v118, 0x110, v118
	v_lshl_add_u32 v118, v107, 4, v118
	v_lshlrev_b32_e32 v119, 6, v104
	v_add_u32_e32 v119, 0x8800, v119
	s_waitcnt lgkmcnt(0)
	s_cmp_eq_u32 s28, 0x100
	s_cbranch_scc1 .Lp3r_entry
	s_cmp_ge_u32 s20, 0x100
	s_cbranch_scc1 .Lp3_notab
	s_cmp_lt_u32 s20, 0x80
	s_cselect_b32 s22, s40, s42
	s_cselect_b32 s23, s41, s43
	v_and_b32_e32 v109, 0x7f, v0
	v_lshlrev_b32_e32 v109, 4, v109
	global_load_dwordx4 v[216:219], v109, s[22:23]
	v_lshlrev_b32_e32 v110, 4, v0
	v_add_u32_e32 v110, 0x8800, v110
	s_waitcnt vmcnt(0)
	ds_write_b128 v110, v[216:219]

; __device__ __forceinline__ unsigned pk2(float lo, float hi) { f32x2_t v = {lo, hi}; bf16x2_t b = __builtin_convertvector(v, bf16x2_t); return __builtin_bit_cast(unsigned, b); }
; __device__ __forceinline__ float bf_lo(unsigned u) { return __uint_as_float(u << 16); }
; __device__ __forceinline__ float bf_hi(unsigned u) { return __uint_as_float(u & 0xffff0000u); }
; __global__ void __launch_bounds__(512, 2) mega_fwd(Args a) {
;     ...
;         const int ustep = (G == 256) ? 1 : G;
;         const int jx = vcu & 31;
;         const int u0 = (G == 256) ? (256 * (vcu >> 5) + (jx < 16 ? 7 * jx : 112 + 9 * (jx - 16))) : vcu;
;         const int ucnt = (G == 256) ? (bx < 128 ? 7 : 9) : (vcu < 2048 ? (2047 - vcu) / G + 1 : 0);
;         if (ucnt > 0) { const bf16_t* vp = Z + ((size_t)(u0 >> 3) * 128 + jt) * NZ + 1024 + (u0 & 7) * 64 + 16 * qd; r0 = *(const u32x4*)vp; r1 = *(const u32x4*)(vp + 8);
; #pragma unroll
;             for (int e4 = 0; e4 < 4; ++e4) { lgv[e4] = *(const f32x4*)(KA->gm_ln_g + (u0 & 7) * 64 + 16 * qd + 4 * e4); lbv[e4] = *(const f32x4*)(KA->gm_ln_b + (u0 & 7) * 64 + 16 * qd + 4 * e4); } }
;     ...
;                 bf16_t* op = AO + (t0 + itok) * DM + 512 + h * 64 + 32 * dblk + 4 * hi;
; #pragma unroll
;                 for (int g = 0; g < 4; ++g) {
;                     u32x2 w; w.x = pk2(bf_lo(uu[g].x) * (acc[4 * g] + bsp), bf_hi(uu[g].x) * (acc[4 * g + 1] + bsp)); w.y = pk2(bf_lo(uu[g].y) * (acc[4 * g + 2] + bsp), bf_hi(uu[g].y) * (acc[4 * g + 3] + bsp));
;                     *(u32x2*)(op + 8 * g) = w;
;                 }
.Lp3_halfl1:
	s_lshr_b32 s21, s39, 3
	s_and_b32 s22, s39, 7
	s_lshl_b32 s24, s21, 18
	s_lshl_b32 s25, s22, 7
	s_add_u32 s24, s24, s25
	s_add_u32 s24, s24, 0x14a00000
	s_add_u32 s48, s8, s24
	s_addc_u32 s49, s9, 0
	s_waitcnt vmcnt(0)
	v_lshlrev_b32_e32 v200, 16, v80
	v_and_b32_e32 v201, s38, v80
	v_lshlrev_b32_e32 v202, 16, v81
	v_and_b32_e32 v203, s38, v81
	v_lshlrev_b32_e32 v204, 16, v82
	v_and_b32_e32 v205, s38, v82
	v_lshlrev_b32_e32 v206, 16, v83
	v_and_b32_e32 v207, s38, v83
	v_lshlrev_b32_e32 v208, 16, v84
	v_and_b32_e32 v209, s38, v84
	v_lshlrev_b32_e32 v210, 16, v85
	v_and_b32_e32 v211, s38, v85
	v_lshlrev_b32_e32 v212, 16, v86
	v_and_b32_e32 v213, s38, v86
	v_lshlrev_b32_e32 v214, 16, v87
	v_and_b32_e32 v215, s38, v87
	s_nop 7
	v_pk_add_f32 v[0:1], v[0:1], v[34:35] op_sel_hi:[1,0]
	v_pk_add_f32 v[2:3], v[2:3], v[34:35] op_sel_hi:[1,0]
	v_pk_add_f32 v[4:5], v[4:5], v[34:35] op_sel_hi:[1,0]
	v_pk_add_f32 v[6:7], v[6:7], v[34:35] op_sel_hi:[1,0]
	v_pk_add_f32 v[8:9], v[8:9], v[34:35] op_sel_hi:[1,0]
	v_pk_add_f32 v[10:11], v[10:11], v[34:35] op_sel_hi:[1,0]
	v_pk_add_f32 v[12:13], v[12:13], v[34:35] op_sel_hi:[1,0]
	v_pk_add_f32 v[14:15], v[14:15], v[34:35] op_sel_hi:[1,0]
	v_pk_mul_f32 v[0:1], v[0:1], v[200:201]
	v_pk_mul_f32 v[2:3], v[2:3], v[202:203]
	v_pk_mul_f32 v[4:5], v[4:5], v[204:205]
	v_pk_mul_f32 v[6:7], v[6:7], v[206:207]
	v_pk_mul_f32 v[8:9], v[8:9], v[208:209]
	v_pk_mul_f32 v[10:11], v[10:11], v[210:211]
	v_pk_mul_f32 v[12:13], v[12:13], v[212:213]
	v_pk_mul_f32 v[14:15], v[14:15], v[214:215]
	v_cvt_pk_bf16_f32 v224, v0, v1
	v_cvt_pk_bf16_f32 v225, v2, v3
	v_cvt_pk_bf16_f32 v226, v4, v5
	v_cvt_pk_bf16_f32 v227, v6, v7
	v_cvt_pk_bf16_f32 v228, v8, v9
	v_cvt_pk_bf16_f32 v229, v10, v11
	v_cvt_pk_bf16_f32 v230, v12, v13
	v_cvt_pk_bf16_f32 v231, v14, v15
	global_store_dwordx2 v116, v[224:225], s[48:49]
	global_store_dwordx2 v116, v[226:227], s[48:49] offset:16
	global_store_dwordx2 v116, v[228:229], s[48:49] offset:32
	global_store_dwordx2 v116, v[230:231], s[48:49] offset:48
	s_branch .Lp3_done
.Lp3r_entry:
	s_and_b32 s10, s54, 31
	s_and_b32 s22, s10, 7
	s_lshr_b32 s11, s10, 3
	s_mul_i32 s12, s11, 7
	s_mul_i32 s13, s11, 9
	s_sub_u32 s13, s13, 4
	s_cmp_lt_u32 s11, 2
	s_cselect_b32 s12, s12, s13
	s_and_b32 s39, s39, 0xffffff00
	s_lshr_b32 s39, s39, 3
	s_add_u32 s21, s39, s12
	s_mul_i32 s24, s21, 0x60000
	s_lshl_b32 s25, s22, 7
	s_add_u32 s24, s24, s25
	s_add_u32 s24, s24, 0x6000000
	s_add_u32 s26, s8, s24
	s_addc_u32 s27, s9, 0
	s_lshl_b32 s24, s21, 18
	s_add_u32 s24, s24, s25
	s_add_u32 s24, s24, 0x14a00000
	s_add_u32 s48, s8, s24
	s_addc_u32 s49, s9, 0
	s_lshl_b32 s24, s22, 15
	s_add_u32 s24, s24, 0x180000
	s_add_u32 s36, s8, s24
	s_addc_u32 s37, s9, 0
	s_lshl_b32 s24, s22, 9
	s_add_u32 s46, s16, s24
	s_addc_u32 s47, s17, 0
	s_lshl_b32 s24, s22, 8
	s_add_u32 s50, s40, s24
	s_addc_u32 s51, s41, 0
	s_add_u32 s52, s42, s24
	s_addc_u32 s53, s43, 0
	v_lshlrev_b32_e32 v109, 6, v104
	global_load_dwordx4 v[120:123], v114, s[36:37]
	global_load_dwordx4 v[124:127], v114, s[36:37] offset:32
	global_load_dwordx4 v[128:131], v114, s[36:37] offset:64
	global_load_dwordx4 v[132:135], v114, s[36:37] offset:96
	global_load_dwordx4 v[136:139], v114, s[36:37] offset:128
	global_load_dwordx4 v[140:143], v114, s[36:37] offset:160
	global_load_dwordx4 v[144:147], v114, s[36:37] offset:192
	global_load_dwordx4 v[148:151], v114, s[36:37] offset:224
	global_load_dword v32, v115, s[46:47]
	global_load_dwordx4 v[152:155], v109, s[50:51]
	global_load_dwordx4 v[156:159], v109, s[50:51] offset:16
	global_load_dwordx4 v[160:163], v109, s[50:51] offset:32
	global_load_dwordx4 v[164:167], v109, s[50:51] offset:48
	global_load_dwordx4 v[168:171], v109, s[52:53]
	global_load_dwordx4 v[172:175], v109, s[52:53] offset:16
	global_load_dwordx4 v[176:179], v109, s[52:53] offset:32
	global_load_dwordx4 v[180:183], v109, s[52:53] offset:48
	s_mov_b32 s45, 0
	global_load_dwordx4 v[16:19], v112, s[26:27]
	global_load_dwordx4 v[20:23], v112, s[26:27] offset:16
	global_load_dwordx2 v[24:25], v113, s[26:27]
	global_load_dwordx2 v[26:27], v113, s[26:27] offset:16
	global_load_dwordx2 v[28:29], v113, s[26:27] offset:32
	global_load_dwordx2 v[30:31], v113, s[26:27] offset:48
	s_add_u32 s26, s26, 0x60000
	s_addc_u32 s27, s27, 0
	s_cmp_lt_u32 s18, 2
	s_cbranch_scc1 .Lp3r_tail0
	global_load_dwordx4 v[40:43], v112, s[26:27]
	global_load_dwordx4 v[44:47], v112, s[26:27] offset:16
	global_load_dwordx2 v[48:49], v113, s[26:27]
	global_load_dwordx2 v[50:51], v113, s[26:27] offset:16
	global_load_dwordx2 v[52:53], v113, s[26:27] offset:32
	global_load_dwordx2 v[54:55], v113, s[26:27] offset:48
	s_add_u32 s26, s26, 0x60000
	s_addc_u32 s27, s27, 0
; __global__ void __launch_bounds__(512, 2) mega_fwd(Args a) {
;     ...
;             {
;                 float xv[16];
;                 xv[0] = bf_lo(r0.x); xv[1] = bf_hi(r0.x); xv[2] = bf_lo(r0.y); xv[3] = bf_hi(r0.y); xv[4] = bf_lo(r0.z); xv[5] = bf_hi(r0.z); xv[6] = bf_lo(r0.w); xv[7] = bf_hi(r0.w);
;                 xv[8] = bf_lo(r1.x); xv[9] = bf_hi(r1.x); xv[10] = bf_lo(r1.y); xv[11] = bf_hi(r1.y); xv[12] = bf_lo(r1.z); xv[13] = bf_hi(r1.z); xv[14] = bf_lo(r1.w); xv[15] = bf_hi(r1.w);
;                 float sm = 0.f;
; #pragma unroll
;                 for (int e = 0; e < 16; ++e) sm += xv[e];
;                 sm += __shfl_xor(sm, 1); sm += __shfl_xor(sm, 2);
;                 const float mu = sm * (1.0f / 64.0f); float q = 0.f;
; #pragma unroll
;                 for (int e = 0; e < 16; ++e) { xv[e] -= mu; q += xv[e] * xv[e]; }
;                 q += __shfl_xor(q, 1); q += __shfl_xor(q, 2);
;                 const float rstd = rsqrtf(q * (1.0f / 64.0f) + EPS);
; #pragma unroll
;                 for (int e = 0; e < 16; ++e) { const float y = xv[e] * rstd * lgv[e >> 2][e & 3] + lbv[e >> 2][e & 3]; VLT[(16 * qd + e) * VLP + jt] = (bf16_t)(pk2(y, 0.f) & 0xffffu); }
;             }
;             const int un = u + ustep;
;             if (ui + 1 < ucnt) { const bf16_t* vp = Z + ((size_t)(un >> 3) * 128 + jt) * NZ + 1024 + (un & 7) * 64 + 16 * qd; r0 = *(const u32x4*)vp; r1 = *(const u32x4*)(vp + 8);
; #pragma unroll
;                 for (int e4 = 0; e4 < 4; ++e4) { lgv[e4] = *(const f32x4*)(KA->gm_ln_g + (un & 7) * 64 + 16 * qd + 4 * e4); lbv[e4] = *(const f32x4*)(KA->gm_ln_b + (un & 7) * 64 + 16 * qd + 4 * e4); } }
;             const int itok = 32 * iblk + r32;
;             const bf16_t* up = Z + (t0 + itok) * NZ + 512 + h * 64 + 32 * dblk + 4 * hi;
;             u32x2 uu[4];
; #pragma unroll
;             for (int g = 0; g < 4; ++g) uu[g] = *(const u32x2*)(up + 8 * g);
;             const float bsp = KA->b_spatial[h * 128 + itok];
;             bf16x8 wf[8];
;             { const bf16_t* wp = WSP + ((size_t)h * 128 + itok) * 128 + 8 * hi;
; #pragma unroll
;               for (int s = 0; s < 8; ++s) if (s < 4 || iblk >= 2) wf[s] = *(const bf16x8*)(wp + 16 * s); }
;             __syncthreads();
;             {
;                 f32x16 acc;
; #pragma unroll
;                 for (int r = 0; r < 16; ++r) acc[r] = 0.f;
.Lp3r_body0:
	s_add_u32 s44, s45, 2
	s_cmp_lt_u32 s44, s18
	s_cbranch_scc0 .Lp3r_tail0
	global_load_dwordx4 v[56:59], v112, s[26:27]
	global_load_dwordx4 v[60:63], v112, s[26:27] offset:16
	global_load_dwordx2 v[64:65], v113, s[26:27]
	global_load_dwordx2 v[66:67], v113, s[26:27] offset:16
	global_load_dwordx2 v[68:69], v113, s[26:27] offset:32
	global_load_dwordx2 v[70:71], v113, s[26:27] offset:48
	s_add_u32 s26, s26, 0x60000
	s_addc_u32 s27, s27, 0
	s_waitcnt vmcnt(17)
	v_lshlrev_b32_e32 v200, 16, v16
	v_and_b32_e32 v201, s38, v16
	v_lshlrev_b32_e32 v202, 16, v17
	v_and_b32_e32 v203, s38, v17
	v_lshlrev_b32_e32 v204, 16, v18
	v_and_b32_e32 v205, s38, v18
	v_lshlrev_b32_e32 v206, 16, v19
	v_and_b32_e32 v207, s38, v19
	s_waitcnt vmcnt(16)
	v_lshlrev_b32_e32 v208, 16, v20
	v_and_b32_e32 v209, s38, v20
	v_lshlrev_b32_e32 v210, 16, v21
	v_and_b32_e32 v211, s38, v21
	v_lshlrev_b32_e32 v212, 16, v22
	v_and_b32_e32 v213, s38, v22
	v_lshlrev_b32_e32 v214, 16, v23
	v_and_b32_e32 v215, s38, v23
	v_pk_add_f32 v[216:217], v[200:201], v[202:203]
	v_pk_add_f32 v[218:219], v[204:205], v[206:207]
	v_pk_add_f32 v[220:221], v[208:209], v[210:211]
	v_pk_add_f32 v[222:223], v[212:213], v[214:215]
	v_pk_add_f32 v[216:217], v[216:217], v[218:219]
	v_pk_add_f32 v[220:221], v[220:221], v[222:223]
	v_pk_add_f32 v[216:217], v[216:217], v[220:221]
	v_add_f32_e32 v216, v216, v217
	s_nop 1
	v_add_f32_dpp v217, v216, v216 quad_perm:[1,0,3,2] row_mask:0xf bank_mask:0xf
	s_nop 1
	v_add_f32_dpp v216, v217, v217 quad_perm:[2,3,0,1] row_mask:0xf bank_mask:0xf
	v_mul_f32_e32 v216, 0xbc800000, v216
	v_pk_add_f32 v[200:201], v[200:201], v[216:217] op_sel_hi:[1,0]
	v_pk_add_f32 v[202:203], v[202:203], v[216:217] op_sel_hi:[1,0]
	v_pk_add_f32 v[204:205], v[204:205], v[216:217] op_sel_hi:[1,0]
	v_pk_add_f32 v[206:207], v[206:207], v[216:217] op_sel_hi:[1,0]
	v_pk_add_f32 v[208:209], v[208:209], v[216:217] op_sel_hi:[1,0]
	v_pk_add_f32 v[210:211], v[210:211], v[216:217] op_sel_hi:[1,0]
	v_pk_add_f32 v[212:213], v[212:213], v[216:217] op_sel_hi:[1,0]
	v_pk_add_f32 v[214:215], v[214:215], v[216:217] op_sel_hi:[1,0]
	v_pk_mul_f32 v[218:219], v[200:201], v[200:201]
	v_pk_mul_f32 v[220:221], v[202:203], v[202:203]
	v_pk_fma_f32 v[218:219], v[204:205], v[204:205], v[218:219]
	v_pk_fma_f32 v[220:221], v[206:207], v[206:207], v[220:221]
	v_pk_fma_f32 v[218:219], v[208:209], v[208:209], v[218:219]
	v_pk_fma_f32 v[220:221], v[210:211], v[210:211], v[220:221]
	v_pk_fma_f32 v[218:219], v[212:213], v[212:213], v[218:219]
	v_pk_fma_f32 v[220:221], v[214:215], v[214:215], v[220:221]
	v_pk_add_f32 v[218:219], v[218:219], v[220:221]
	v_add_f32_e32 v218, v218, v219
	s_nop 1
	v_add_f32_dpp v219, v218, v218 quad_perm:[1,0,3,2] row_mask:0xf bank_mask:0xf
	s_nop 1
	v_add_f32_dpp v218, v219, v219 quad_perm:[2,3,0,1] row_mask:0xf bank_mask:0xf
	v_fmamk_f32 v218, v218, 0x3c800000, v111
	v_rsq_f32_e32 v218, v218
	s_nop 0
	v_pk_mul_f32 v[200:201], v[200:201], v[218:219] op_sel_hi:[1,0]
	v_pk_mul_f32 v[202:203], v[202:203], v[218:219] op_sel_hi:[1,0]
	v_pk_mul_f32 v[204:205], v[204:205], v[218:219] op_sel_hi:[1,0]
	v_pk_mul_f32 v[206:207], v[206:207], v[218:219] op_sel_hi:[1,0]
	v_pk_mul_f32 v[208:209], v[208:209], v[218:219] op_sel_hi:[1,0]
	v_pk_mul_f32 v[210:211], v[210:211], v[218:219] op_sel_hi:[1,0]
	v_pk_mul_f32 v[212:213], v[212:213], v[218:219] op_sel_hi:[1,0]
	v_pk_mul_f32 v[214:215], v[214:215], v[218:219] op_sel_hi:[1,0]
	v_pk_fma_f32 v[200:201], v[200:201], v[152:153], v[168:169]
	v_pk_fma_f32 v[202:203], v[202:203], v[154:155], v[170:171]
	v_pk_fma_f32 v[204:205], v[204:205], v[156:157], v[172:173]
	v_pk_fma_f32 v[206:207], v[206:207], v[158:159], v[174:175]
	v_pk_fma_f32 v[208:209], v[208:209], v[160:161], v[176:177]
	v_pk_fma_f32 v[210:211], v[210:211], v[162:163], v[178:179]
	v_pk_fma_f32 v[212:213], v[212:213], v[164:165], v[180:181]
	v_pk_fma_f32 v[214:215], v[214:215], v[166:167], v[182:183]
	v_cvt_pk_bf16_f32 v224, v200, v201
	v_cvt_pk_bf16_f32 v225, v202, v203
	v_cvt_pk_bf16_f32 v226, v204, v205
	v_cvt_pk_bf16_f32 v227, v206, v207
	v_cvt_pk_bf16_f32 v228, v208, v209
	v_cvt_pk_bf16_f32 v229, v210, v211
	v_cvt_pk_bf16_f32 v230, v212, v213
	v_cvt_pk_bf16_f32 v231, v214, v215
	ds_write_b16 v117, v224 offset:0
	ds_write_b16_d16_hi v117, v224 offset:272
	ds_write_b16 v117, v225 offset:544
	ds_write_b16_d16_hi v117, v225 offset:816
	ds_write_b16 v117, v226 offset:1088
	ds_write_b16_d16_hi v117, v226 offset:1360
	ds_write_b16 v117, v227 offset:1632
	ds_write_b16_d16_hi v117, v227 offset:1904
	ds_write_b16 v117, v228 offset:2176
	ds_write_b16_d16_hi v117, v228 offset:2448
	ds_write_b16 v117, v229 offset:2720
	ds_write_b16_d16_hi v117, v229 offset:2992
	ds_write_b16 v117, v230 offset:3264
	ds_write_b16_d16_hi v117, v230 offset:3536
	ds_write_b16 v117, v231 offset:3808
	ds_write_b16_d16_hi v117, v231 offset:4080
	s_waitcnt lgkmcnt(0)
	s_barrier
	ds_read_b128 v[88:91], v118 offset:0
	ds_read_b128 v[92:95], v118 offset:32
	ds_read_b128 v[96:99], v118 offset:64
	ds_read_b128 v[100:103], v118 offset:96
	s_waitcnt lgkmcnt(3)
	v_mfma_f32_32x32x16_bf16 v[0:15], v[88:91], v[120:123], 0
	s_waitcnt lgkmcnt(2)
	v_mfma_f32_32x32x16_bf16 v[0:15], v[92:95], v[124:127], v[0:15]
	s_waitcnt lgkmcnt(1)
	v_mfma_f32_32x32x16_bf16 v[0:15], v[96:99], v[128:131], v[0:15]
	s_waitcnt lgkmcnt(0)
	v_mfma_f32_32x32x16_bf16 v[0:15], v[100:103], v[132:135], v[0:15]
	s_cmp_lt_u32 s20, 0x100
	s_cbranch_scc1 .Lp3r_half0
	ds_read_b128 v[88:91], v118 offset:128
	ds_read_b128 v[92:95], v118 offset:160
	ds_read_b128 v[96:99], v118 offset:192
	ds_read_b128 v[100:103], v118 offset:224
	s_waitcnt lgkmcnt(3)
	v_mfma_f32_32x32x16_bf16 v[0:15], v[88:91], v[136:139], v[0:15]
	s_waitcnt lgkmcnt(2)
	v_mfma_f32_32x32x16_bf16 v[0:15], v[92:95], v[140:143], v[0:15]
	s_waitcnt lgkmcnt(1)
	v_mfma_f32_32x32x16_bf16 v[0:15], v[96:99], v[144:147], v[0:15]
	s_waitcnt lgkmcnt(0)
	v_mfma_f32_32x32x16_bf16 v[0:15], v[100:103], v[148:151], v[0:15]
; __device__ __forceinline__ unsigned pk2(float lo, float hi) { f32x2_t v = {lo, hi}; bf16x2_t b = __builtin_convertvector(v, bf16x2_t); return __builtin_bit_cast(unsigned, b); }
; __device__ __forceinline__ float bf_lo(unsigned u) { return __uint_as_float(u << 16); }
; __device__ __forceinline__ float bf_hi(unsigned u) { return __uint_as_float(u & 0xffff0000u); }
; __global__ void __launch_bounds__(512, 2) mega_fwd(Args a) {
;     ...
;             {
;                 float xv[16];
;                 xv[0] = bf_lo(r0.x); xv[1] = bf_hi(r0.x); xv[2] = bf_lo(r0.y); xv[3] = bf_hi(r0.y); xv[4] = bf_lo(r0.z); xv[5] = bf_hi(r0.z); xv[6] = bf_lo(r0.w); xv[7] = bf_hi(r0.w);
;                 xv[8] = bf_lo(r1.x); xv[9] = bf_hi(r1.x); xv[10] = bf_lo(r1.y); xv[11] = bf_hi(r1.y); xv[12] = bf_lo(r1.z); xv[13] = bf_hi(r1.z); xv[14] = bf_lo(r1.w); xv[15] = bf_hi(r1.w);
;                 float sm = 0.f;
; #pragma unroll
;                 for (int e = 0; e < 16; ++e) sm += xv[e];
;                 sm += __shfl_xor(sm, 1); sm += __shfl_xor(sm, 2);
;                 const float mu = sm * (1.0f / 64.0f); float q = 0.f;
; #pragma unroll
;                 for (int e = 0; e < 16; ++e) { xv[e] -= mu; q += xv[e] * xv[e]; }
;                 q += __shfl_xor(q, 1); q += __shfl_xor(q, 2);
;                 const float rstd = rsqrtf(q * (1.0f / 64.0f) + EPS);
; #pragma unroll
;                 for (int e = 0; e < 16; ++e) { const float y = xv[e] * rstd * lgv[e >> 2][e & 3] + lbv[e >> 2][e & 3]; VLT[(16 * qd + e) * VLP + jt] = (bf16_t)(pk2(y, 0.f) & 0xffffu); }
;     ...
;                 bf16_t* op = AO + (t0 + itok) * DM + 512 + h * 64 + 32 * dblk + 4 * hi;
; #pragma unroll
;                 for (int g = 0; g < 4; ++g) {
;                     u32x2 w; w.x = pk2(bf_lo(uu[g].x) * (acc[4 * g] + bsp), bf_hi(uu[g].x) * (acc[4 * g + 1] + bsp)); w.y = pk2(bf_lo(uu[g].y) * (acc[4 * g + 2] + bsp), bf_hi(uu[g].y) * (acc[4 * g + 3] + bsp));
;                     *(u32x2*)(op + 8 * g) = w;
;                 }
.Lp3r_half0:
	s_waitcnt vmcnt(12)
	v_lshlrev_b32_e32 v200, 16, v24
	v_and_b32_e32 v201, s38, v24
	v_lshlrev_b32_e32 v202, 16, v25
	v_and_b32_e32 v203, s38, v25
	v_lshlrev_b32_e32 v204, 16, v26
	v_and_b32_e32 v205, s38, v26
	v_lshlrev_b32_e32 v206, 16, v27
	v_and_b32_e32 v207, s38, v27
	v_lshlrev_b32_e32 v208, 16, v28
	v_and_b32_e32 v209, s38, v28
	v_lshlrev_b32_e32 v210, 16, v29
	v_and_b32_e32 v211, s38, v29
	v_lshlrev_b32_e32 v212, 16, v30
	v_and_b32_e32 v213, s38, v30
	v_lshlrev_b32_e32 v214, 16, v31
	v_and_b32_e32 v215, s38, v31
	s_nop 7
	v_pk_add_f32 v[0:1], v[0:1], v[32:33] op_sel_hi:[1,0]
	v_pk_add_f32 v[2:3], v[2:3], v[32:33] op_sel_hi:[1,0]
	v_pk_add_f32 v[4:5], v[4:5], v[32:33] op_sel_hi:[1,0]
	v_pk_add_f32 v[6:7], v[6:7], v[32:33] op_sel_hi:[1,0]
	v_pk_add_f32 v[8:9], v[8:9], v[32:33] op_sel_hi:[1,0]
	v_pk_add_f32 v[10:11], v[10:11], v[32:33] op_sel_hi:[1,0]
	v_pk_add_f32 v[12:13], v[12:13], v[32:33] op_sel_hi:[1,0]
	v_pk_add_f32 v[14:15], v[14:15], v[32:33] op_sel_hi:[1,0]
	v_pk_mul_f32 v[0:1], v[0:1], v[200:201]
	v_pk_mul_f32 v[2:3], v[2:3], v[202:203]
	v_pk_mul_f32 v[4:5], v[4:5], v[204:205]
	v_pk_mul_f32 v[6:7], v[6:7], v[206:207]
	v_pk_mul_f32 v[8:9], v[8:9], v[208:209]
	v_pk_mul_f32 v[10:11], v[10:11], v[210:211]
	v_pk_mul_f32 v[12:13], v[12:13], v[212:213]
	v_pk_mul_f32 v[14:15], v[14:15], v[214:215]
	v_cvt_pk_bf16_f32 v224, v0, v1
	v_cvt_pk_bf16_f32 v225, v2, v3
	v_cvt_pk_bf16_f32 v226, v4, v5
	v_cvt_pk_bf16_f32 v227, v6, v7
	v_cvt_pk_bf16_f32 v228, v8, v9
	v_cvt_pk_bf16_f32 v229, v10, v11
	v_cvt_pk_bf16_f32 v230, v12, v13
	v_cvt_pk_bf16_f32 v231, v14, v15
	global_store_dwordx2 v116, v[224:225], s[48:49]
	global_store_dwordx2 v116, v[226:227], s[48:49] offset:16
	global_store_dwordx2 v116, v[228:229], s[48:49] offset:32
	global_store_dwordx2 v116, v[230:231], s[48:49] offset:48
	s_add_u32 s48, s48, 0x40000
	s_addc_u32 s49, s49, 0
	s_add_u32 s45, s45, 1
.Lp3r_body1:
	s_add_u32 s44, s45, 2
	s_cmp_lt_u32 s44, s18
	s_cbranch_scc0 .Lp3r_tail1
	global_load_dwordx4 v[16:19], v112, s[26:27]
	global_load_dwordx4 v[20:23], v112, s[26:27] offset:16
	global_load_dwordx2 v[24:25], v113, s[26:27]
	global_load_dwordx2 v[26:27], v113, s[26:27] offset:16
	global_load_dwordx2 v[28:29], v113, s[26:27] offset:32
	global_load_dwordx2 v[30:31], v113, s[26:27] offset:48
	s_add_u32 s26, s26, 0x60000
	s_addc_u32 s27, s27, 0
	s_waitcnt vmcnt(17)
	v_lshlrev_b32_e32 v200, 16, v40
	v_and_b32_e32 v201, s38, v40
	v_lshlrev_b32_e32 v202, 16, v41
	v_and_b32_e32 v203, s38, v41
	v_lshlrev_b32_e32 v204, 16, v42
	v_and_b32_e32 v205, s38, v42
	v_lshlrev_b32_e32 v206, 16, v43
	v_and_b32_e32 v207, s38, v43
	s_waitcnt vmcnt(16)
	v_lshlrev_b32_e32 v208, 16, v44
	v_and_b32_e32 v209, s38, v44
	v_lshlrev_b32_e32 v210, 16, v45
	v_and_b32_e32 v211, s38, v45
	v_lshlrev_b32_e32 v212, 16, v46
	v_and_b32_e32 v213, s38, v46
	v_lshlrev_b32_e32 v214, 16, v47
	v_and_b32_e32 v215, s38, v47
	v_pk_add_f32 v[216:217], v[200:201], v[202:203]
	v_pk_add_f32 v[218:219], v[204:205], v[206:207]
	v_pk_add_f32 v[220:221], v[208:209], v[210:211]
	v_pk_add_f32 v[222:223], v[212:213], v[214:215]
	v_pk_add_f32 v[216:217], v[216:217], v[218:219]
	v_pk_add_f32 v[220:221], v[220:221], v[222:223]
	v_pk_add_f32 v[216:217], v[216:217], v[220:221]
	v_add_f32_e32 v216, v216, v217
	s_nop 1
	v_add_f32_dpp v217, v216, v216 quad_perm:[1,0,3,2] row_mask:0xf bank_mask:0xf
	s_nop 1
	v_add_f32_dpp v216, v217, v217 quad_perm:[2,3,0,1] row_mask:0xf bank_mask:0xf
	v_mul_f32_e32 v216, 0xbc800000, v216
	v_pk_add_f32 v[200:201], v[200:201], v[216:217] op_sel_hi:[1,0]
	v_pk_add_f32 v[202:203], v[202:203], v[216:217] op_sel_hi:[1,0]
	v_pk_add_f32 v[204:205], v[204:205], v[216:217] op_sel_hi:[1,0]
	v_pk_add_f32 v[206:207], v[206:207], v[216:217] op_sel_hi:[1,0]
	v_pk_add_f32 v[208:209], v[208:209], v[216:217] op_sel_hi:[1,0]
	v_pk_add_f32 v[210:211], v[210:211], v[216:217] op_sel_hi:[1,0]
	v_pk_add_f32 v[212:213], v[212:213], v[216:217] op_sel_hi:[1,0]
	v_pk_add_f32 v[214:215], v[214:215], v[216:217] op_sel_hi:[1,0]
	v_pk_mul_f32 v[218:219], v[200:201], v[200:201]
	v_pk_mul_f32 v[220:221], v[202:203], v[202:203]
	v_pk_fma_f32 v[218:219], v[204:205], v[204:205], v[218:219]
	v_pk_fma_f32 v[220:221], v[206:207], v[206:207], v[220:221]
	v_pk_fma_f32 v[218:219], v[208:209], v[208:209], v[218:219]
	v_pk_fma_f32 v[220:221], v[210:211], v[210:211], v[220:221]
	v_pk_fma_f32 v[218:219], v[212:213], v[212:213], v[218:219]
	v_pk_fma_f32 v[220:221], v[214:215], v[214:215], v[220:221]
	v_pk_add_f32 v[218:219], v[218:219], v[220:221]
	v_add_f32_e32 v218, v218, v219
	s_nop 1
	v_add_f32_dpp v219, v218, v218 quad_perm:[1,0,3,2] row_mask:0xf bank_mask:0xf
	s_nop 1
	v_add_f32_dpp v218, v219, v219 quad_perm:[2,3,0,1] row_mask:0xf bank_mask:0xf
	v_fmamk_f32 v218, v218, 0x3c800000, v111
	v_rsq_f32_e32 v218, v218
	s_nop 0
	v_pk_mul_f32 v[200:201], v[200:201], v[218:219] op_sel_hi:[1,0]
	v_pk_mul_f32 v[202:203], v[202:203], v[218:219] op_sel_hi:[1,0]
	v_pk_mul_f32 v[204:205], v[204:205], v[218:219] op_sel_hi:[1,0]
	v_pk_mul_f32 v[206:207], v[206:207], v[218:219] op_sel_hi:[1,0]
	v_pk_mul_f32 v[208:209], v[208:209], v[218:219] op_sel_hi:[1,0]
	v_pk_mul_f32 v[210:211], v[210:211], v[218:219] op_sel_hi:[1,0]
	v_pk_mul_f32 v[212:213], v[212:213], v[218:219] op_sel_hi:[1,0]
	v_pk_mul_f32 v[214:215], v[214:215], v[218:219] op_sel_hi:[1,0]
	v_pk_fma_f32 v[200:201], v[200:201], v[152:153], v[168:169]
	v_pk_fma_f32 v[202:203], v[202:203], v[154:155], v[170:171]
	v_pk_fma_f32 v[204:205], v[204:205], v[156:157], v[172:173]
	v_pk_fma_f32 v[206:207], v[206:207], v[158:159], v[174:175]
	v_pk_fma_f32 v[208:209], v[208:209], v[160:161], v[176:177]
	v_pk_fma_f32 v[210:211], v[210:211], v[162:163], v[178:179]
	v_pk_fma_f32 v[212:213], v[212:213], v[164:165], v[180:181]
	v_pk_fma_f32 v[214:215], v[214:215], v[166:167], v[182:183]
	v_cvt_pk_bf16_f32 v224, v200, v201
	v_cvt_pk_bf16_f32 v225, v202, v203
	v_cvt_pk_bf16_f32 v226, v204, v205
	v_cvt_pk_bf16_f32 v227, v206, v207
	v_cvt_pk_bf16_f32 v228, v208, v209
	v_cvt_pk_bf16_f32 v229, v210, v211
	v_cvt_pk_bf16_f32 v230, v212, v213
	v_cvt_pk_bf16_f32 v231, v214, v215
	ds_write_b16 v117, v224 offset:17408
	ds_write_b16_d16_hi v117, v224 offset:17680
	ds_write_b16 v117, v225 offset:17952
	ds_write_b16_d16_hi v117, v225 offset:18224
	ds_write_b16 v117, v226 offset:18496
	ds_write_b16_d16_hi v117, v226 offset:18768
	ds_write_b16 v117, v227 offset:19040
	ds_write_b16_d16_hi v117, v227 offset:19312
	ds_write_b16 v117, v228 offset:19584
	ds_write_b16_d16_hi v117, v228 offset:19856
	ds_write_b16 v117, v229 offset:20128
	ds_write_b16_d16_hi v117, v229 offset:20400
	ds_write_b16 v117, v230 offset:20672
	ds_write_b16_d16_hi v117, v230 offset:20944
	ds_write_b16 v117, v231 offset:21216
	ds_write_b16_d16_hi v117, v231 offset:21488
	s_waitcnt lgkmcnt(0)
	s_barrier
; #define LAS __attribute__((address_space(3)))
; __device__ __forceinline__ unsigned pk2(float lo, float hi) { f32x2_t v = {lo, hi}; bf16x2_t b = __builtin_convertvector(v, bf16x2_t); return __builtin_bit_cast(unsigned, b); }
; __device__ __forceinline__ float bf_lo(unsigned u) { return __uint_as_float(u << 16); }
; __device__ __forceinline__ float bf_hi(unsigned u) { return __uint_as_float(u & 0xffff0000u); }
; __global__ void __launch_bounds__(512, 2) mega_fwd(Args a) {
;     ...
;             {
;                 float xv[16];
;                 xv[0] = bf_lo(r0.x); xv[1] = bf_hi(r0.x); xv[2] = bf_lo(r0.y); xv[3] = bf_hi(r0.y); xv[4] = bf_lo(r0.z); xv[5] = bf_hi(r0.z); xv[6] = bf_lo(r0.w); xv[7] = bf_hi(r0.w);
;                 xv[8] = bf_lo(r1.x); xv[9] = bf_hi(r1.x); xv[10] = bf_lo(r1.y); xv[11] = bf_hi(r1.y); xv[12] = bf_lo(r1.z); xv[13] = bf_hi(r1.z); xv[14] = bf_lo(r1.w); xv[15] = bf_hi(r1.w);
;                 float sm = 0.f;
; #pragma unroll
;                 for (int e = 0; e < 16; ++e) sm += xv[e];
;                 sm += __shfl_xor(sm, 1); sm += __shfl_xor(sm, 2);
;                 const float mu = sm * (1.0f / 64.0f); float q = 0.f;
; #pragma unroll
;                 for (int e = 0; e < 16; ++e) { xv[e] -= mu; q += xv[e] * xv[e]; }
;                 q += __shfl_xor(q, 1); q += __shfl_xor(q, 2);
;                 const float rstd = rsqrtf(q * (1.0f / 64.0f) + EPS);
;     ...
;             __syncthreads();
;             {
;                 f32x16 acc;
; #pragma unroll
;                 for (int r = 0; r < 16; ++r) acc[r] = 0.f;
;                 const LAS bf16_t* vl = VLT + (32 * dblk + r32) * VLP + 8 * hi;
; #pragma unroll
;                 for (int s = 0; s < 8; ++s) if (s < 4 || iblk >= 2) {
;                     const bf16x8 vf = *(const LAS bf16x8*)(vl + 16 * s);
;                     acc = __builtin_amdgcn_mfma_f32_32x32x16_bf16(vf, wf[s], acc, 0, 0, 0);
;                 }
;                 bf16_t* op = AO + (t0 + itok) * DM + 512 + h * 64 + 32 * dblk + 4 * hi;
; #pragma unroll
;                 for (int g = 0; g < 4; ++g) {
;                     u32x2 w; w.x = pk2(bf_lo(uu[g].x) * (acc[4 * g] + bsp), bf_hi(uu[g].x) * (acc[4 * g + 1] + bsp)); w.y = pk2(bf_lo(uu[g].y) * (acc[4 * g + 2] + bsp), bf_hi(uu[g].y) * (acc[4 * g + 3] + bsp));
;                     *(u32x2*)(op + 8 * g) = w;
;                 }
	ds_read_b128 v[88:91], v118 offset:17408
	ds_read_b128 v[92:95], v118 offset:17440
	ds_read_b128 v[96:99], v118 offset:17472
	ds_read_b128 v[100:103], v118 offset:17504
	s_waitcnt lgkmcnt(3)
	v_mfma_f32_32x32x16_bf16 v[0:15], v[88:91], v[120:123], 0
	s_waitcnt lgkmcnt(2)
	v_mfma_f32_32x32x16_bf16 v[0:15], v[92:95], v[124:127], v[0:15]
	s_waitcnt lgkmcnt(1)
	v_mfma_f32_32x32x16_bf16 v[0:15], v[96:99], v[128:131], v[0:15]
	s_waitcnt lgkmcnt(0)
	v_mfma_f32_32x32x16_bf16 v[0:15], v[100:103], v[132:135], v[0:15]
	s_cmp_lt_u32 s20, 0x100
	s_cbranch_scc1 .Lp3r_half1
	ds_read_b128 v[88:91], v118 offset:17536
	ds_read_b128 v[92:95], v118 offset:17568
	ds_read_b128 v[96:99], v118 offset:17600
	ds_read_b128 v[100:103], v118 offset:17632
	s_waitcnt lgkmcnt(3)
	v_mfma_f32_32x32x16_bf16 v[0:15], v[88:91], v[136:139], v[0:15]
	s_waitcnt lgkmcnt(2)
	v_mfma_f32_32x32x16_bf16 v[0:15], v[92:95], v[140:143], v[0:15]
	s_waitcnt lgkmcnt(1)
	v_mfma_f32_32x32x16_bf16 v[0:15], v[96:99], v[144:147], v[0:15]
	s_waitcnt lgkmcnt(0)
	v_mfma_f32_32x32x16_bf16 v[0:15], v[100:103], v[148:151], v[0:15]
.Lp3r_half1:
	s_waitcnt vmcnt(12)
	v_lshlrev_b32_e32 v200, 16, v48
	v_and_b32_e32 v201, s38, v48
	v_lshlrev_b32_e32 v202, 16, v49
	v_and_b32_e32 v203, s38, v49
	v_lshlrev_b32_e32 v204, 16, v50
	v_and_b32_e32 v205, s38, v50
	v_lshlrev_b32_e32 v206, 16, v51
	v_and_b32_e32 v207, s38, v51
	v_lshlrev_b32_e32 v208, 16, v52
	v_and_b32_e32 v209, s38, v52
	v_lshlrev_b32_e32 v210, 16, v53
	v_and_b32_e32 v211, s38, v53
	v_lshlrev_b32_e32 v212, 16, v54
	v_and_b32_e32 v213, s38, v54
	v_lshlrev_b32_e32 v214, 16, v55
	v_and_b32_e32 v215, s38, v55
	s_nop 7
	v_pk_add_f32 v[0:1], v[0:1], v[32:33] op_sel_hi:[1,0]
	v_pk_add_f32 v[2:3], v[2:3], v[32:33] op_sel_hi:[1,0]
	v_pk_add_f32 v[4:5], v[4:5], v[32:33] op_sel_hi:[1,0]
	v_pk_add_f32 v[6:7], v[6:7], v[32:33] op_sel_hi:[1,0]
	v_pk_add_f32 v[8:9], v[8:9], v[32:33] op_sel_hi:[1,0]
	v_pk_add_f32 v[10:11], v[10:11], v[32:33] op_sel_hi:[1,0]
	v_pk_add_f32 v[12:13], v[12:13], v[32:33] op_sel_hi:[1,0]
	v_pk_add_f32 v[14:15], v[14:15], v[32:33] op_sel_hi:[1,0]
	v_pk_mul_f32 v[0:1], v[0:1], v[200:201]
	v_pk_mul_f32 v[2:3], v[2:3], v[202:203]
	v_pk_mul_f32 v[4:5], v[4:5], v[204:205]
	v_pk_mul_f32 v[6:7], v[6:7], v[206:207]
	v_pk_mul_f32 v[8:9], v[8:9], v[208:209]
	v_pk_mul_f32 v[10:11], v[10:11], v[210:211]
	v_pk_mul_f32 v[12:13], v[12:13], v[212:213]
	v_pk_mul_f32 v[14:15], v[14:15], v[214:215]
	v_cvt_pk_bf16_f32 v224, v0, v1
	v_cvt_pk_bf16_f32 v225, v2, v3
	v_cvt_pk_bf16_f32 v226, v4, v5
	v_cvt_pk_bf16_f32 v227, v6, v7
	v_cvt_pk_bf16_f32 v228, v8, v9
	v_cvt_pk_bf16_f32 v229, v10, v11
	v_cvt_pk_bf16_f32 v230, v12, v13
	v_cvt_pk_bf16_f32 v231, v14, v15
	global_store_dwordx2 v116, v[224:225], s[48:49]
	global_store_dwordx2 v116, v[226:227], s[48:49] offset:16
	global_store_dwordx2 v116, v[228:229], s[48:49] offset:32
	global_store_dwordx2 v116, v[230:231], s[48:49] offset:48
	s_add_u32 s48, s48, 0x40000
	s_addc_u32 s49, s49, 0
	s_add_u32 s45, s45, 1
.Lp3r_body2:
	s_add_u32 s44, s45, 2
	s_cmp_lt_u32 s44, s18
	s_cbranch_scc0 .Lp3r_tail2
	global_load_dwordx4 v[40:43], v112, s[26:27]
	global_load_dwordx4 v[44:47], v112, s[26:27] offset:16
	global_load_dwordx2 v[48:49], v113, s[26:27]
	global_load_dwordx2 v[50:51], v113, s[26:27] offset:16
	global_load_dwordx2 v[52:53], v113, s[26:27] offset:32
	global_load_dwordx2 v[54:55], v113, s[26:27] offset:48
	s_add_u32 s26, s26, 0x60000
	s_addc_u32 s27, s27, 0
	s_waitcnt vmcnt(17)
	v_lshlrev_b32_e32 v200, 16, v56
	v_and_b32_e32 v201, s38, v56
	v_lshlrev_b32_e32 v202, 16, v57
	v_and_b32_e32 v203, s38, v57
	v_lshlrev_b32_e32 v204, 16, v58
	v_and_b32_e32 v205, s38, v58
	v_lshlrev_b32_e32 v206, 16, v59
	v_and_b32_e32 v207, s38, v59
	s_waitcnt vmcnt(16)
	v_lshlrev_b32_e32 v208, 16, v60
	v_and_b32_e32 v209, s38, v60
	v_lshlrev_b32_e32 v210, 16, v61
	v_and_b32_e32 v211, s38, v61
	v_lshlrev_b32_e32 v212, 16, v62
	v_and_b32_e32 v213, s38, v62
	v_lshlrev_b32_e32 v214, 16, v63
	v_and_b32_e32 v215, s38, v63
	v_pk_add_f32 v[216:217], v[200:201], v[202:203]
	v_pk_add_f32 v[218:219], v[204:205], v[206:207]
	v_pk_add_f32 v[220:221], v[208:209], v[210:211]
	v_pk_add_f32 v[222:223], v[212:213], v[214:215]
	v_pk_add_f32 v[216:217], v[216:217], v[218:219]
	v_pk_add_f32 v[220:221], v[220:221], v[222:223]
	v_pk_add_f32 v[216:217], v[216:217], v[220:221]
	v_add_f32_e32 v216, v216, v217
	s_nop 1
	v_add_f32_dpp v217, v216, v216 quad_perm:[1,0,3,2] row_mask:0xf bank_mask:0xf
	s_nop 1
	v_add_f32_dpp v216, v217, v217 quad_perm:[2,3,0,1] row_mask:0xf bank_mask:0xf
	v_mul_f32_e32 v216, 0xbc800000, v216
	v_pk_add_f32 v[200:201], v[200:201], v[216:217] op_sel_hi:[1,0]
	v_pk_add_f32 v[202:203], v[202:203], v[216:217] op_sel_hi:[1,0]
	v_pk_add_f32 v[204:205], v[204:205], v[216:217] op_sel_hi:[1,0]
	v_pk_add_f32 v[206:207], v[206:207], v[216:217] op_sel_hi:[1,0]
	v_pk_add_f32 v[208:209], v[208:209], v[216:217] op_sel_hi:[1,0]
	v_pk_add_f32 v[210:211], v[210:211], v[216:217] op_sel_hi:[1,0]
	v_pk_add_f32 v[212:213], v[212:213], v[216:217] op_sel_hi:[1,0]
	v_pk_add_f32 v[214:215], v[214:215], v[216:217] op_sel_hi:[1,0]
	v_pk_mul_f32 v[218:219], v[200:201], v[200:201]
	v_pk_mul_f32 v[220:221], v[202:203], v[202:203]
	v_pk_fma_f32 v[218:219], v[204:205], v[204:205], v[218:219]
	v_pk_fma_f32 v[220:221], v[206:207], v[206:207], v[220:221]
	v_pk_fma_f32 v[218:219], v[208:209], v[208:209], v[218:219]
	v_pk_fma_f32 v[220:221], v[210:211], v[210:211], v[220:221]
	v_pk_fma_f32 v[218:219], v[212:213], v[212:213], v[218:219]
	v_pk_fma_f32 v[220:221], v[214:215], v[214:215], v[220:221]
	v_pk_add_f32 v[218:219], v[218:219], v[220:221]
	v_add_f32_e32 v218, v218, v219
; #define LAS __attribute__((address_space(3)))
; __global__ void __launch_bounds__(512, 2) mega_fwd(Args a) {
;     ...
;                 const float rstd = rsqrtf(q * (1.0f / 64.0f) + EPS);
; #pragma unroll
;                 for (int e = 0; e < 16; ++e) { const float y = xv[e] * rstd * lgv[e >> 2][e & 3] + lbv[e >> 2][e & 3]; VLT[(16 * qd + e) * VLP + jt] = (bf16_t)(pk2(y, 0.f) & 0xffffu); }
;             }
;             const int un = u + ustep;
;             if (ui + 1 < ucnt) { const bf16_t* vp = Z + ((size_t)(un >> 3) * 128 + jt) * NZ + 1024 + (un & 7) * 64 + 16 * qd; r0 = *(const u32x4*)vp; r1 = *(const u32x4*)(vp + 8);
; #pragma unroll
;                 for (int e4 = 0; e4 < 4; ++e4) { lgv[e4] = *(const f32x4*)(KA->gm_ln_g + (un & 7) * 64 + 16 * qd + 4 * e4); lbv[e4] = *(const f32x4*)(KA->gm_ln_b + (un & 7) * 64 + 16 * qd + 4 * e4); } }
;             const int itok = 32 * iblk + r32;
;             const bf16_t* up = Z + (t0 + itok) * NZ + 512 + h * 64 + 32 * dblk + 4 * hi;
;             u32x2 uu[4];
; #pragma unroll
;             for (int g = 0; g < 4; ++g) uu[g] = *(const u32x2*)(up + 8 * g);
;             const float bsp = KA->b_spatial[h * 128 + itok];
;             bf16x8 wf[8];
;             { const bf16_t* wp = WSP + ((size_t)h * 128 + itok) * 128 + 8 * hi;
; #pragma unroll
;               for (int s = 0; s < 8; ++s) if (s < 4 || iblk >= 2) wf[s] = *(const bf16x8*)(wp + 16 * s); }
;             __syncthreads();
;             {
;                 f32x16 acc;
; #pragma unroll
;                 for (int r = 0; r < 16; ++r) acc[r] = 0.f;
;                 const LAS bf16_t* vl = VLT + (32 * dblk + r32) * VLP + 8 * hi;
; #pragma unroll
;                 for (int s = 0; s < 8; ++s) if (s < 4 || iblk >= 2) {
;                     const bf16x8 vf = *(const LAS bf16x8*)(vl + 16 * s);
;                     acc = __builtin_amdgcn_mfma_f32_32x32x16_bf16(vf, wf[s], acc, 0, 0, 0);
;                 }
;                 bf16_t* op = AO + (t0 + itok) * DM + 512 + h * 64 + 32 * dblk + 4 * hi;
; #pragma unroll
;                 for (int g = 0; g < 4; ++g) {
;                     u32x2 w; w.x = pk2(bf_lo(uu[g].x) * (acc[4 * g] + bsp), bf_hi(uu[g].x) * (acc[4 * g + 1] + bsp)); w.y = pk2(bf_lo(uu[g].y) * (acc[4 * g + 2] + bsp), bf_hi(uu[g].y) * (acc[4 * g + 3] + bsp));
;                     *(u32x2*)(op + 8 * g) = w;
;                 }
	s_nop 1
	v_add_f32_dpp v219, v218, v218 quad_perm:[1,0,3,2] row_mask:0xf bank_mask:0xf
	s_nop 1
	v_add_f32_dpp v218, v219, v219 quad_perm:[2,3,0,1] row_mask:0xf bank_mask:0xf
	v_fmamk_f32 v218, v218, 0x3c800000, v111
	v_rsq_f32_e32 v218, v218
	s_nop 0
	v_pk_mul_f32 v[200:201], v[200:201], v[218:219] op_sel_hi:[1,0]
	v_pk_mul_f32 v[202:203], v[202:203], v[218:219] op_sel_hi:[1,0]
	v_pk_mul_f32 v[204:205], v[204:205], v[218:219] op_sel_hi:[1,0]
	v_pk_mul_f32 v[206:207], v[206:207], v[218:219] op_sel_hi:[1,0]
	v_pk_mul_f32 v[208:209], v[208:209], v[218:219] op_sel_hi:[1,0]
	v_pk_mul_f32 v[210:211], v[210:211], v[218:219] op_sel_hi:[1,0]
	v_pk_mul_f32 v[212:213], v[212:213], v[218:219] op_sel_hi:[1,0]
	v_pk_mul_f32 v[214:215], v[214:215], v[218:219] op_sel_hi:[1,0]
	v_pk_fma_f32 v[200:201], v[200:201], v[152:153], v[168:169]
	v_pk_fma_f32 v[202:203], v[202:203], v[154:155], v[170:171]
	v_pk_fma_f32 v[204:205], v[204:205], v[156:157], v[172:173]
	v_pk_fma_f32 v[206:207], v[206:207], v[158:159], v[174:175]
	v_pk_fma_f32 v[208:209], v[208:209], v[160:161], v[176:177]
	v_pk_fma_f32 v[210:211], v[210:211], v[162:163], v[178:179]
	v_pk_fma_f32 v[212:213], v[212:213], v[164:165], v[180:181]
	v_pk_fma_f32 v[214:215], v[214:215], v[166:167], v[182:183]
	v_cvt_pk_bf16_f32 v224, v200, v201
	v_cvt_pk_bf16_f32 v225, v202, v203
	v_cvt_pk_bf16_f32 v226, v204, v205
	v_cvt_pk_bf16_f32 v227, v206, v207
	v_cvt_pk_bf16_f32 v228, v208, v209
	v_cvt_pk_bf16_f32 v229, v210, v211
	v_cvt_pk_bf16_f32 v230, v212, v213
	v_cvt_pk_bf16_f32 v231, v214, v215
	ds_write_b16 v117, v224 offset:34816
	ds_write_b16_d16_hi v117, v224 offset:35088
	ds_write_b16 v117, v225 offset:35360
	ds_write_b16_d16_hi v117, v225 offset:35632
	ds_write_b16 v117, v226 offset:35904
	ds_write_b16_d16_hi v117, v226 offset:36176
	ds_write_b16 v117, v227 offset:36448
	ds_write_b16_d16_hi v117, v227 offset:36720
	ds_write_b16 v117, v228 offset:36992
	ds_write_b16_d16_hi v117, v228 offset:37264
	ds_write_b16 v117, v229 offset:37536
	ds_write_b16_d16_hi v117, v229 offset:37808
	ds_write_b16 v117, v230 offset:38080
	ds_write_b16_d16_hi v117, v230 offset:38352
	ds_write_b16 v117, v231 offset:38624
	ds_write_b16_d16_hi v117, v231 offset:38896
	s_waitcnt lgkmcnt(0)
	s_barrier
	ds_read_b128 v[88:91], v118 offset:34816
	ds_read_b128 v[92:95], v118 offset:34848
	ds_read_b128 v[96:99], v118 offset:34880
	ds_read_b128 v[100:103], v118 offset:34912
	s_waitcnt lgkmcnt(3)
	v_mfma_f32_32x32x16_bf16 v[0:15], v[88:91], v[120:123], 0
	s_waitcnt lgkmcnt(2)
	v_mfma_f32_32x32x16_bf16 v[0:15], v[92:95], v[124:127], v[0:15]
	s_waitcnt lgkmcnt(1)
	v_mfma_f32_32x32x16_bf16 v[0:15], v[96:99], v[128:131], v[0:15]
	s_waitcnt lgkmcnt(0)
	v_mfma_f32_32x32x16_bf16 v[0:15], v[100:103], v[132:135], v[0:15]
	s_cmp_lt_u32 s20, 0x100
	s_cbranch_scc1 .Lp3r_half2
	ds_read_b128 v[88:91], v118 offset:34944
	ds_read_b128 v[92:95], v118 offset:34976
	ds_read_b128 v[96:99], v118 offset:35008
	ds_read_b128 v[100:103], v118 offset:35040
	s_waitcnt lgkmcnt(3)
	v_mfma_f32_32x32x16_bf16 v[0:15], v[88:91], v[136:139], v[0:15]
	s_waitcnt lgkmcnt(2)
	v_mfma_f32_32x32x16_bf16 v[0:15], v[92:95], v[140:143], v[0:15]
	s_waitcnt lgkmcnt(1)
	v_mfma_f32_32x32x16_bf16 v[0:15], v[96:99], v[144:147], v[0:15]
	s_waitcnt lgkmcnt(0)
	v_mfma_f32_32x32x16_bf16 v[0:15], v[100:103], v[148:151], v[0:15]
.Lp3r_half2:
	s_waitcnt vmcnt(12)
	v_lshlrev_b32_e32 v200, 16, v64
	v_and_b32_e32 v201, s38, v64
	v_lshlrev_b32_e32 v202, 16, v65
	v_and_b32_e32 v203, s38, v65
	v_lshlrev_b32_e32 v204, 16, v66
	v_and_b32_e32 v205, s38, v66
	v_lshlrev_b32_e32 v206, 16, v67
	v_and_b32_e32 v207, s38, v67
	v_lshlrev_b32_e32 v208, 16, v68
	v_and_b32_e32 v209, s38, v68
	v_lshlrev_b32_e32 v210, 16, v69
	v_and_b32_e32 v211, s38, v69
	v_lshlrev_b32_e32 v212, 16, v70
	v_and_b32_e32 v213, s38, v70
	v_lshlrev_b32_e32 v214, 16, v71
	v_and_b32_e32 v215, s38, v71
	s_nop 7
	v_pk_add_f32 v[0:1], v[0:1], v[32:33] op_sel_hi:[1,0]
	v_pk_add_f32 v[2:3], v[2:3], v[32:33] op_sel_hi:[1,0]
	v_pk_add_f32 v[4:5], v[4:5], v[32:33] op_sel_hi:[1,0]
	v_pk_add_f32 v[6:7], v[6:7], v[32:33] op_sel_hi:[1,0]
	v_pk_add_f32 v[8:9], v[8:9], v[32:33] op_sel_hi:[1,0]
	v_pk_add_f32 v[10:11], v[10:11], v[32:33] op_sel_hi:[1,0]
	v_pk_add_f32 v[12:13], v[12:13], v[32:33] op_sel_hi:[1,0]
	v_pk_add_f32 v[14:15], v[14:15], v[32:33] op_sel_hi:[1,0]
	v_pk_mul_f32 v[0:1], v[0:1], v[200:201]
	v_pk_mul_f32 v[2:3], v[2:3], v[202:203]
	v_pk_mul_f32 v[4:5], v[4:5], v[204:205]
	v_pk_mul_f32 v[6:7], v[6:7], v[206:207]
	v_pk_mul_f32 v[8:9], v[8:9], v[208:209]
	v_pk_mul_f32 v[10:11], v[10:11], v[210:211]
	v_pk_mul_f32 v[12:13], v[12:13], v[212:213]
	v_pk_mul_f32 v[14:15], v[14:15], v[214:215]
	v_cvt_pk_bf16_f32 v224, v0, v1
	v_cvt_pk_bf16_f32 v225, v2, v3
	v_cvt_pk_bf16_f32 v226, v4, v5
	v_cvt_pk_bf16_f32 v227, v6, v7
	v_cvt_pk_bf16_f32 v228, v8, v9
	v_cvt_pk_bf16_f32 v229, v10, v11
	v_cvt_pk_bf16_f32 v230, v12, v13
	v_cvt_pk_bf16_f32 v231, v14, v15
	global_store_dwordx2 v116, v[224:225], s[48:49]
	global_store_dwordx2 v116, v[226:227], s[48:49] offset:16
	global_store_dwordx2 v116, v[228:229], s[48:49] offset:32
	global_store_dwordx2 v116, v[230:231], s[48:49] offset:48
	s_add_u32 s48, s48, 0x40000
	s_addc_u32 s49, s49, 0
	s_add_u32 s45, s45, 1
	s_branch .Lp3r_body0
; __global__ void __launch_bounds__(512, 2) mega_fwd(Args a) {
;     ...
;             {
;                 float xv[16];
;                 xv[0] = bf_lo(r0.x); xv[1] = bf_hi(r0.x); xv[2] = bf_lo(r0.y); xv[3] = bf_hi(r0.y); xv[4] = bf_lo(r0.z); xv[5] = bf_hi(r0.z); xv[6] = bf_lo(r0.w); xv[7] = bf_hi(r0.w);
;                 xv[8] = bf_lo(r1.x); xv[9] = bf_hi(r1.x); xv[10] = bf_lo(r1.y); xv[11] = bf_hi(r1.y); xv[12] = bf_lo(r1.z); xv[13] = bf_hi(r1.z); xv[14] = bf_lo(r1.w); xv[15] = bf_hi(r1.w);
;                 float sm = 0.f;
; #pragma unroll
;                 for (int e = 0; e < 16; ++e) sm += xv[e];
;                 sm += __shfl_xor(sm, 1); sm += __shfl_xor(sm, 2);
;                 const float mu = sm * (1.0f / 64.0f); float q = 0.f;
; #pragma unroll
;                 for (int e = 0; e < 16; ++e) { xv[e] -= mu; q += xv[e] * xv[e]; }
;                 q += __shfl_xor(q, 1); q += __shfl_xor(q, 2);
;                 const float rstd = rsqrtf(q * (1.0f / 64.0f) + EPS);
; #pragma unroll
;                 for (int e = 0; e < 16; ++e) { const float y = xv[e] * rstd * lgv[e >> 2][e & 3] + lbv[e >> 2][e & 3]; VLT[(16 * qd + e) * VLP + jt] = (bf16_t)(pk2(y, 0.f) & 0xffffu); }
;             }
;             const int un = u + ustep;
;             if (ui + 1 < ucnt) { const bf16_t* vp = Z + ((size_t)(un >> 3) * 128 + jt) * NZ + 1024 + (un & 7) * 64 + 16 * qd; r0 = *(const u32x4*)vp; r1 = *(const u32x4*)(vp + 8);
; #pragma unroll
;                 for (int e4 = 0; e4 < 4; ++e4) { lgv[e4] = *(const f32x4*)(KA->gm_ln_g + (un & 7) * 64 + 16 * qd + 4 * e4); lbv[e4] = *(const f32x4*)(KA->gm_ln_b + (un & 7) * 64 + 16 * qd + 4 * e4); } }
;             const int itok = 32 * iblk + r32;
;             const bf16_t* up = Z + (t0 + itok) * NZ + 512 + h * 64 + 32 * dblk + 4 * hi;
;             u32x2 uu[4];
; #pragma unroll
;             for (int g = 0; g < 4; ++g) uu[g] = *(const u32x2*)(up + 8 * g);
;             const float bsp = KA->b_spatial[h * 128 + itok];
;             bf16x8 wf[8];
;             { const bf16_t* wp = WSP + ((size_t)h * 128 + itok) * 128 + 8 * hi;
; #pragma unroll
;               for (int s = 0; s < 8; ++s) if (s < 4 || iblk >= 2) wf[s] = *(const bf16x8*)(wp + 16 * s); }
;             __syncthreads();
;             {
;                 f32x16 acc;
; #pragma unroll
;                 for (int r = 0; r < 16; ++r) acc[r] = 0.f;
.Lp3r_tail0:
	s_waitcnt vmcnt(5)
	v_lshlrev_b32_e32 v200, 16, v16
	v_and_b32_e32 v201, s38, v16
	v_lshlrev_b32_e32 v202, 16, v17
	v_and_b32_e32 v203, s38, v17
	v_lshlrev_b32_e32 v204, 16, v18
	v_and_b32_e32 v205, s38, v18
	v_lshlrev_b32_e32 v206, 16, v19
	v_and_b32_e32 v207, s38, v19
	s_waitcnt vmcnt(4)
	v_lshlrev_b32_e32 v208, 16, v20
	v_and_b32_e32 v209, s38, v20
	v_lshlrev_b32_e32 v210, 16, v21
	v_and_b32_e32 v211, s38, v21
	v_lshlrev_b32_e32 v212, 16, v22
	v_and_b32_e32 v213, s38, v22
	v_lshlrev_b32_e32 v214, 16, v23
	v_and_b32_e32 v215, s38, v23
	v_pk_add_f32 v[216:217], v[200:201], v[202:203]
	v_pk_add_f32 v[218:219], v[204:205], v[206:207]
	v_pk_add_f32 v[220:221], v[208:209], v[210:211]
	v_pk_add_f32 v[222:223], v[212:213], v[214:215]
	v_pk_add_f32 v[216:217], v[216:217], v[218:219]
	v_pk_add_f32 v[220:221], v[220:221], v[222:223]
	v_pk_add_f32 v[216:217], v[216:217], v[220:221]
	v_add_f32_e32 v216, v216, v217
	s_nop 1
	v_add_f32_dpp v217, v216, v216 quad_perm:[1,0,3,2] row_mask:0xf bank_mask:0xf
	s_nop 1
	v_add_f32_dpp v216, v217, v217 quad_perm:[2,3,0,1] row_mask:0xf bank_mask:0xf
	v_mul_f32_e32 v216, 0xbc800000, v216
	v_pk_add_f32 v[200:201], v[200:201], v[216:217] op_sel_hi:[1,0]
	v_pk_add_f32 v[202:203], v[202:203], v[216:217] op_sel_hi:[1,0]
	v_pk_add_f32 v[204:205], v[204:205], v[216:217] op_sel_hi:[1,0]
	v_pk_add_f32 v[206:207], v[206:207], v[216:217] op_sel_hi:[1,0]
	v_pk_add_f32 v[208:209], v[208:209], v[216:217] op_sel_hi:[1,0]
	v_pk_add_f32 v[210:211], v[210:211], v[216:217] op_sel_hi:[1,0]
	v_pk_add_f32 v[212:213], v[212:213], v[216:217] op_sel_hi:[1,0]
	v_pk_add_f32 v[214:215], v[214:215], v[216:217] op_sel_hi:[1,0]
	v_pk_mul_f32 v[218:219], v[200:201], v[200:201]
	v_pk_mul_f32 v[220:221], v[202:203], v[202:203]
	v_pk_fma_f32 v[218:219], v[204:205], v[204:205], v[218:219]
	v_pk_fma_f32 v[220:221], v[206:207], v[206:207], v[220:221]
	v_pk_fma_f32 v[218:219], v[208:209], v[208:209], v[218:219]
	v_pk_fma_f32 v[220:221], v[210:211], v[210:211], v[220:221]
	v_pk_fma_f32 v[218:219], v[212:213], v[212:213], v[218:219]
	v_pk_fma_f32 v[220:221], v[214:215], v[214:215], v[220:221]
	v_pk_add_f32 v[218:219], v[218:219], v[220:221]
	v_add_f32_e32 v218, v218, v219
	s_nop 1
	v_add_f32_dpp v219, v218, v218 quad_perm:[1,0,3,2] row_mask:0xf bank_mask:0xf
	s_nop 1
	v_add_f32_dpp v218, v219, v219 quad_perm:[2,3,0,1] row_mask:0xf bank_mask:0xf
	v_fmamk_f32 v218, v218, 0x3c800000, v111
	v_rsq_f32_e32 v218, v218
	s_nop 0
	v_pk_mul_f32 v[200:201], v[200:201], v[218:219] op_sel_hi:[1,0]
	v_pk_mul_f32 v[202:203], v[202:203], v[218:219] op_sel_hi:[1,0]
	v_pk_mul_f32 v[204:205], v[204:205], v[218:219] op_sel_hi:[1,0]
	v_pk_mul_f32 v[206:207], v[206:207], v[218:219] op_sel_hi:[1,0]
	v_pk_mul_f32 v[208:209], v[208:209], v[218:219] op_sel_hi:[1,0]
	v_pk_mul_f32 v[210:211], v[210:211], v[218:219] op_sel_hi:[1,0]
	v_pk_mul_f32 v[212:213], v[212:213], v[218:219] op_sel_hi:[1,0]
	v_pk_mul_f32 v[214:215], v[214:215], v[218:219] op_sel_hi:[1,0]
	v_pk_fma_f32 v[200:201], v[200:201], v[152:153], v[168:169]
	v_pk_fma_f32 v[202:203], v[202:203], v[154:155], v[170:171]
	v_pk_fma_f32 v[204:205], v[204:205], v[156:157], v[172:173]
	v_pk_fma_f32 v[206:207], v[206:207], v[158:159], v[174:175]
	v_pk_fma_f32 v[208:209], v[208:209], v[160:161], v[176:177]
	v_pk_fma_f32 v[210:211], v[210:211], v[162:163], v[178:179]
	v_pk_fma_f32 v[212:213], v[212:213], v[164:165], v[180:181]
	v_pk_fma_f32 v[214:215], v[214:215], v[166:167], v[182:183]
	v_cvt_pk_bf16_f32 v224, v200, v201
	v_cvt_pk_bf16_f32 v225, v202, v203
	v_cvt_pk_bf16_f32 v226, v204, v205
	v_cvt_pk_bf16_f32 v227, v206, v207
	v_cvt_pk_bf16_f32 v228, v208, v209
	v_cvt_pk_bf16_f32 v229, v210, v211
	v_cvt_pk_bf16_f32 v230, v212, v213
	v_cvt_pk_bf16_f32 v231, v214, v215
	ds_write_b16 v117, v224 offset:0
	ds_write_b16_d16_hi v117, v224 offset:272
	ds_write_b16 v117, v225 offset:544
	ds_write_b16_d16_hi v117, v225 offset:816
	ds_write_b16 v117, v226 offset:1088
	ds_write_b16_d16_hi v117, v226 offset:1360
	ds_write_b16 v117, v227 offset:1632
	ds_write_b16_d16_hi v117, v227 offset:1904
	ds_write_b16 v117, v228 offset:2176
	ds_write_b16_d16_hi v117, v228 offset:2448
	ds_write_b16 v117, v229 offset:2720
	ds_write_b16_d16_hi v117, v229 offset:2992
	ds_write_b16 v117, v230 offset:3264
	ds_write_b16_d16_hi v117, v230 offset:3536
	ds_write_b16 v117, v231 offset:3808
	ds_write_b16_d16_hi v117, v231 offset:4080
	s_waitcnt lgkmcnt(0)
	s_barrier
	ds_read_b128 v[88:91], v118 offset:0
	ds_read_b128 v[92:95], v118 offset:32
	ds_read_b128 v[96:99], v118 offset:64
	ds_read_b128 v[100:103], v118 offset:96
	s_waitcnt lgkmcnt(3)
	v_mfma_f32_32x32x16_bf16 v[0:15], v[88:91], v[120:123], 0
	s_waitcnt lgkmcnt(2)
	v_mfma_f32_32x32x16_bf16 v[0:15], v[92:95], v[124:127], v[0:15]
	s_waitcnt lgkmcnt(1)
	v_mfma_f32_32x32x16_bf16 v[0:15], v[96:99], v[128:131], v[0:15]
	s_waitcnt lgkmcnt(0)
	v_mfma_f32_32x32x16_bf16 v[0:15], v[100:103], v[132:135], v[0:15]
	s_cmp_lt_u32 s20, 0x100
	s_cbranch_scc1 .Lp3r_halft0
	ds_read_b128 v[88:91], v118 offset:128
	ds_read_b128 v[92:95], v118 offset:160
	ds_read_b128 v[96:99], v118 offset:192
	ds_read_b128 v[100:103], v118 offset:224
	s_waitcnt lgkmcnt(3)
	v_mfma_f32_32x32x16_bf16 v[0:15], v[88:91], v[136:139], v[0:15]
	s_waitcnt lgkmcnt(2)
	v_mfma_f32_32x32x16_bf16 v[0:15], v[92:95], v[140:143], v[0:15]
	s_waitcnt lgkmcnt(1)
	v_mfma_f32_32x32x16_bf16 v[0:15], v[96:99], v[144:147], v[0:15]
	s_waitcnt lgkmcnt(0)
	v_mfma_f32_32x32x16_bf16 v[0:15], v[100:103], v[148:151], v[0:15]
; __device__ __forceinline__ unsigned pk2(float lo, float hi) { f32x2_t v = {lo, hi}; bf16x2_t b = __builtin_convertvector(v, bf16x2_t); return __builtin_bit_cast(unsigned, b); }
; __device__ __forceinline__ float bf_lo(unsigned u) { return __uint_as_float(u << 16); }
; __device__ __forceinline__ float bf_hi(unsigned u) { return __uint_as_float(u & 0xffff0000u); }
; __global__ void __launch_bounds__(512, 2) mega_fwd(Args a) {
;     ...
;             {
;                 float xv[16];
;                 xv[0] = bf_lo(r0.x); xv[1] = bf_hi(r0.x); xv[2] = bf_lo(r0.y); xv[3] = bf_hi(r0.y); xv[4] = bf_lo(r0.z); xv[5] = bf_hi(r0.z); xv[6] = bf_lo(r0.w); xv[7] = bf_hi(r0.w);
;                 xv[8] = bf_lo(r1.x); xv[9] = bf_hi(r1.x); xv[10] = bf_lo(r1.y); xv[11] = bf_hi(r1.y); xv[12] = bf_lo(r1.z); xv[13] = bf_hi(r1.z); xv[14] = bf_lo(r1.w); xv[15] = bf_hi(r1.w);
;                 float sm = 0.f;
; #pragma unroll
;                 for (int e = 0; e < 16; ++e) sm += xv[e];
;                 sm += __shfl_xor(sm, 1); sm += __shfl_xor(sm, 2);
;                 const float mu = sm * (1.0f / 64.0f); float q = 0.f;
; #pragma unroll
;                 for (int e = 0; e < 16; ++e) { xv[e] -= mu; q += xv[e] * xv[e]; }
;                 q += __shfl_xor(q, 1); q += __shfl_xor(q, 2);
;                 const float rstd = rsqrtf(q * (1.0f / 64.0f) + EPS);
; #pragma unroll
;                 for (int e = 0; e < 16; ++e) { const float y = xv[e] * rstd * lgv[e >> 2][e & 3] + lbv[e >> 2][e & 3]; VLT[(16 * qd + e) * VLP + jt] = (bf16_t)(pk2(y, 0.f) & 0xffffu); }
;     ...
;                 bf16_t* op = AO + (t0 + itok) * DM + 512 + h * 64 + 32 * dblk + 4 * hi;
; #pragma unroll
;                 for (int g = 0; g < 4; ++g) {
;                     u32x2 w; w.x = pk2(bf_lo(uu[g].x) * (acc[4 * g] + bsp), bf_hi(uu[g].x) * (acc[4 * g + 1] + bsp)); w.y = pk2(bf_lo(uu[g].y) * (acc[4 * g + 2] + bsp), bf_hi(uu[g].y) * (acc[4 * g + 3] + bsp));
;                     *(u32x2*)(op + 8 * g) = w;
;                 }
.Lp3r_halft0:
	s_waitcnt vmcnt(0)
	v_lshlrev_b32_e32 v200, 16, v24
	v_and_b32_e32 v201, s38, v24
	v_lshlrev_b32_e32 v202, 16, v25
	v_and_b32_e32 v203, s38, v25
	v_lshlrev_b32_e32 v204, 16, v26
	v_and_b32_e32 v205, s38, v26
	v_lshlrev_b32_e32 v206, 16, v27
	v_and_b32_e32 v207, s38, v27
	v_lshlrev_b32_e32 v208, 16, v28
	v_and_b32_e32 v209, s38, v28
	v_lshlrev_b32_e32 v210, 16, v29
	v_and_b32_e32 v211, s38, v29
	v_lshlrev_b32_e32 v212, 16, v30
	v_and_b32_e32 v213, s38, v30
	v_lshlrev_b32_e32 v214, 16, v31
	v_and_b32_e32 v215, s38, v31
	s_nop 7
	v_pk_add_f32 v[0:1], v[0:1], v[32:33] op_sel_hi:[1,0]
	v_pk_add_f32 v[2:3], v[2:3], v[32:33] op_sel_hi:[1,0]
	v_pk_add_f32 v[4:5], v[4:5], v[32:33] op_sel_hi:[1,0]
	v_pk_add_f32 v[6:7], v[6:7], v[32:33] op_sel_hi:[1,0]
	v_pk_add_f32 v[8:9], v[8:9], v[32:33] op_sel_hi:[1,0]
	v_pk_add_f32 v[10:11], v[10:11], v[32:33] op_sel_hi:[1,0]
	v_pk_add_f32 v[12:13], v[12:13], v[32:33] op_sel_hi:[1,0]
	v_pk_add_f32 v[14:15], v[14:15], v[32:33] op_sel_hi:[1,0]
	v_pk_mul_f32 v[0:1], v[0:1], v[200:201]
	v_pk_mul_f32 v[2:3], v[2:3], v[202:203]
	v_pk_mul_f32 v[4:5], v[4:5], v[204:205]
	v_pk_mul_f32 v[6:7], v[6:7], v[206:207]
	v_pk_mul_f32 v[8:9], v[8:9], v[208:209]
	v_pk_mul_f32 v[10:11], v[10:11], v[210:211]
	v_pk_mul_f32 v[12:13], v[12:13], v[212:213]
	v_pk_mul_f32 v[14:15], v[14:15], v[214:215]
	v_cvt_pk_bf16_f32 v224, v0, v1
	v_cvt_pk_bf16_f32 v225, v2, v3
	v_cvt_pk_bf16_f32 v226, v4, v5
	v_cvt_pk_bf16_f32 v227, v6, v7
	v_cvt_pk_bf16_f32 v228, v8, v9
	v_cvt_pk_bf16_f32 v229, v10, v11
	v_cvt_pk_bf16_f32 v230, v12, v13
	v_cvt_pk_bf16_f32 v231, v14, v15
	global_store_dwordx2 v116, v[224:225], s[48:49]
	global_store_dwordx2 v116, v[226:227], s[48:49] offset:16
	global_store_dwordx2 v116, v[228:229], s[48:49] offset:32
	global_store_dwordx2 v116, v[230:231], s[48:49] offset:48
	s_add_u32 s48, s48, 0x40000
	s_addc_u32 s49, s49, 0
	s_add_u32 s45, s45, 1
	s_cmp_lt_u32 s45, s18
	s_cbranch_scc0 .Lp3_done
.Lp3r_tail1:
	s_waitcnt vmcnt(5)
	v_lshlrev_b32_e32 v200, 16, v40
	v_and_b32_e32 v201, s38, v40
	v_lshlrev_b32_e32 v202, 16, v41
	v_and_b32_e32 v203, s38, v41
	v_lshlrev_b32_e32 v204, 16, v42
	v_and_b32_e32 v205, s38, v42
	v_lshlrev_b32_e32 v206, 16, v43
	v_and_b32_e32 v207, s38, v43
	s_waitcnt vmcnt(4)
	v_lshlrev_b32_e32 v208, 16, v44
	v_and_b32_e32 v209, s38, v44
	v_lshlrev_b32_e32 v210, 16, v45
	v_and_b32_e32 v211, s38, v45
	v_lshlrev_b32_e32 v212, 16, v46
	v_and_b32_e32 v213, s38, v46
	v_lshlrev_b32_e32 v214, 16, v47
	v_and_b32_e32 v215, s38, v47
	v_pk_add_f32 v[216:217], v[200:201], v[202:203]
	v_pk_add_f32 v[218:219], v[204:205], v[206:207]
	v_pk_add_f32 v[220:221], v[208:209], v[210:211]
	v_pk_add_f32 v[222:223], v[212:213], v[214:215]
	v_pk_add_f32 v[216:217], v[216:217], v[218:219]
	v_pk_add_f32 v[220:221], v[220:221], v[222:223]
	v_pk_add_f32 v[216:217], v[216:217], v[220:221]
	v_add_f32_e32 v216, v216, v217
	s_nop 1
	v_add_f32_dpp v217, v216, v216 quad_perm:[1,0,3,2] row_mask:0xf bank_mask:0xf
	s_nop 1
	v_add_f32_dpp v216, v217, v217 quad_perm:[2,3,0,1] row_mask:0xf bank_mask:0xf
	v_mul_f32_e32 v216, 0xbc800000, v216
	v_pk_add_f32 v[200:201], v[200:201], v[216:217] op_sel_hi:[1,0]
	v_pk_add_f32 v[202:203], v[202:203], v[216:217] op_sel_hi:[1,0]
	v_pk_add_f32 v[204:205], v[204:205], v[216:217] op_sel_hi:[1,0]
	v_pk_add_f32 v[206:207], v[206:207], v[216:217] op_sel_hi:[1,0]
	v_pk_add_f32 v[208:209], v[208:209], v[216:217] op_sel_hi:[1,0]
	v_pk_add_f32 v[210:211], v[210:211], v[216:217] op_sel_hi:[1,0]
	v_pk_add_f32 v[212:213], v[212:213], v[216:217] op_sel_hi:[1,0]
	v_pk_add_f32 v[214:215], v[214:215], v[216:217] op_sel_hi:[1,0]
	v_pk_mul_f32 v[218:219], v[200:201], v[200:201]
	v_pk_mul_f32 v[220:221], v[202:203], v[202:203]
	v_pk_fma_f32 v[218:219], v[204:205], v[204:205], v[218:219]
	v_pk_fma_f32 v[220:221], v[206:207], v[206:207], v[220:221]
	v_pk_fma_f32 v[218:219], v[208:209], v[208:209], v[218:219]
	v_pk_fma_f32 v[220:221], v[210:211], v[210:211], v[220:221]
	v_pk_fma_f32 v[218:219], v[212:213], v[212:213], v[218:219]
	v_pk_fma_f32 v[220:221], v[214:215], v[214:215], v[220:221]
	v_pk_add_f32 v[218:219], v[218:219], v[220:221]
	v_add_f32_e32 v218, v218, v219
	s_nop 1
	v_add_f32_dpp v219, v218, v218 quad_perm:[1,0,3,2] row_mask:0xf bank_mask:0xf
	s_nop 1
	v_add_f32_dpp v218, v219, v219 quad_perm:[2,3,0,1] row_mask:0xf bank_mask:0xf
	v_fmamk_f32 v218, v218, 0x3c800000, v111
	v_rsq_f32_e32 v218, v218
	s_nop 0
	v_pk_mul_f32 v[200:201], v[200:201], v[218:219] op_sel_hi:[1,0]
	v_pk_mul_f32 v[202:203], v[202:203], v[218:219] op_sel_hi:[1,0]
	v_pk_mul_f32 v[204:205], v[204:205], v[218:219] op_sel_hi:[1,0]
	v_pk_mul_f32 v[206:207], v[206:207], v[218:219] op_sel_hi:[1,0]
	v_pk_mul_f32 v[208:209], v[208:209], v[218:219] op_sel_hi:[1,0]
	v_pk_mul_f32 v[210:211], v[210:211], v[218:219] op_sel_hi:[1,0]
	v_pk_mul_f32 v[212:213], v[212:213], v[218:219] op_sel_hi:[1,0]
	v_pk_mul_f32 v[214:215], v[214:215], v[218:219] op_sel_hi:[1,0]
	v_pk_fma_f32 v[200:201], v[200:201], v[152:153], v[168:169]
	v_pk_fma_f32 v[202:203], v[202:203], v[154:155], v[170:171]
	v_pk_fma_f32 v[204:205], v[204:205], v[156:157], v[172:173]
	v_pk_fma_f32 v[206:207], v[206:207], v[158:159], v[174:175]
	v_pk_fma_f32 v[208:209], v[208:209], v[160:161], v[176:177]
	v_pk_fma_f32 v[210:211], v[210:211], v[162:163], v[178:179]
	v_pk_fma_f32 v[212:213], v[212:213], v[164:165], v[180:181]
	v_pk_fma_f32 v[214:215], v[214:215], v[166:167], v[182:183]
	v_cvt_pk_bf16_f32 v224, v200, v201
	v_cvt_pk_bf16_f32 v225, v202, v203
	v_cvt_pk_bf16_f32 v226, v204, v205
	v_cvt_pk_bf16_f32 v227, v206, v207
	v_cvt_pk_bf16_f32 v228, v208, v209
	v_cvt_pk_bf16_f32 v229, v210, v211
	v_cvt_pk_bf16_f32 v230, v212, v213
	v_cvt_pk_bf16_f32 v231, v214, v215
	ds_write_b16 v117, v224 offset:17408
	ds_write_b16_d16_hi v117, v224 offset:17680
	ds_write_b16 v117, v225 offset:17952
	ds_write_b16_d16_hi v117, v225 offset:18224
	ds_write_b16 v117, v226 offset:18496
	ds_write_b16_d16_hi v117, v226 offset:18768
	ds_write_b16 v117, v227 offset:19040
	ds_write_b16_d16_hi v117, v227 offset:19312
	ds_write_b16 v117, v228 offset:19584
	ds_write_b16_d16_hi v117, v228 offset:19856
	ds_write_b16 v117, v229 offset:20128
	ds_write_b16_d16_hi v117, v229 offset:20400
	ds_write_b16 v117, v230 offset:20672
	ds_write_b16_d16_hi v117, v230 offset:20944
	ds_write_b16 v117, v231 offset:21216
	ds_write_b16_d16_hi v117, v231 offset:21488
	s_waitcnt lgkmcnt(0)
	s_barrier
; #define LAS __attribute__((address_space(3)))
; __device__ __forceinline__ unsigned pk2(float lo, float hi) { f32x2_t v = {lo, hi}; bf16x2_t b = __builtin_convertvector(v, bf16x2_t); return __builtin_bit_cast(unsigned, b); }
; __device__ __forceinline__ float bf_lo(unsigned u) { return __uint_as_float(u << 16); }
; __device__ __forceinline__ float bf_hi(unsigned u) { return __uint_as_float(u & 0xffff0000u); }
; __global__ void __launch_bounds__(512, 2) mega_fwd(Args a) {
;     ...
;             {
;                 float xv[16];
;                 xv[0] = bf_lo(r0.x); xv[1] = bf_hi(r0.x); xv[2] = bf_lo(r0.y); xv[3] = bf_hi(r0.y); xv[4] = bf_lo(r0.z); xv[5] = bf_hi(r0.z); xv[6] = bf_lo(r0.w); xv[7] = bf_hi(r0.w);
;                 xv[8] = bf_lo(r1.x); xv[9] = bf_hi(r1.x); xv[10] = bf_lo(r1.y); xv[11] = bf_hi(r1.y); xv[12] = bf_lo(r1.z); xv[13] = bf_hi(r1.z); xv[14] = bf_lo(r1.w); xv[15] = bf_hi(r1.w);
;                 float sm = 0.f;
; #pragma unroll
;                 for (int e = 0; e < 16; ++e) sm += xv[e];
;                 sm += __shfl_xor(sm, 1); sm += __shfl_xor(sm, 2);
;                 const float mu = sm * (1.0f / 64.0f); float q = 0.f;
; #pragma unroll
;                 for (int e = 0; e < 16; ++e) { xv[e] -= mu; q += xv[e] * xv[e]; }
;                 q += __shfl_xor(q, 1); q += __shfl_xor(q, 2);
;                 const float rstd = rsqrtf(q * (1.0f / 64.0f) + EPS);
;     ...
;             __syncthreads();
;             {
;                 f32x16 acc;
; #pragma unroll
;                 for (int r = 0; r < 16; ++r) acc[r] = 0.f;
;                 const LAS bf16_t* vl = VLT + (32 * dblk + r32) * VLP + 8 * hi;
; #pragma unroll
;                 for (int s = 0; s < 8; ++s) if (s < 4 || iblk >= 2) {
;                     const bf16x8 vf = *(const LAS bf16x8*)(vl + 16 * s);
;                     acc = __builtin_amdgcn_mfma_f32_32x32x16_bf16(vf, wf[s], acc, 0, 0, 0);
;                 }
;                 bf16_t* op = AO + (t0 + itok) * DM + 512 + h * 64 + 32 * dblk + 4 * hi;
; #pragma unroll
;                 for (int g = 0; g < 4; ++g) {
;                     u32x2 w; w.x = pk2(bf_lo(uu[g].x) * (acc[4 * g] + bsp), bf_hi(uu[g].x) * (acc[4 * g + 1] + bsp)); w.y = pk2(bf_lo(uu[g].y) * (acc[4 * g + 2] + bsp), bf_hi(uu[g].y) * (acc[4 * g + 3] + bsp));
;                     *(u32x2*)(op + 8 * g) = w;
;                 }
	ds_read_b128 v[88:91], v118 offset:17408
	ds_read_b128 v[92:95], v118 offset:17440
	ds_read_b128 v[96:99], v118 offset:17472
	ds_read_b128 v[100:103], v118 offset:17504
	s_waitcnt lgkmcnt(3)
	v_mfma_f32_32x32x16_bf16 v[0:15], v[88:91], v[120:123], 0
	s_waitcnt lgkmcnt(2)
	v_mfma_f32_32x32x16_bf16 v[0:15], v[92:95], v[124:127], v[0:15]
	s_waitcnt lgkmcnt(1)
	v_mfma_f32_32x32x16_bf16 v[0:15], v[96:99], v[128:131], v[0:15]
	s_waitcnt lgkmcnt(0)
	v_mfma_f32_32x32x16_bf16 v[0:15], v[100:103], v[132:135], v[0:15]
	s_cmp_lt_u32 s20, 0x100
	s_cbranch_scc1 .Lp3r_halft1
	ds_read_b128 v[88:91], v118 offset:17536
	ds_read_b128 v[92:95], v118 offset:17568
	ds_read_b128 v[96:99], v118 offset:17600
	ds_read_b128 v[100:103], v118 offset:17632
	s_waitcnt lgkmcnt(3)
	v_mfma_f32_32x32x16_bf16 v[0:15], v[88:91], v[136:139], v[0:15]
	s_waitcnt lgkmcnt(2)
	v_mfma_f32_32x32x16_bf16 v[0:15], v[92:95], v[140:143], v[0:15]
	s_waitcnt lgkmcnt(1)
	v_mfma_f32_32x32x16_bf16 v[0:15], v[96:99], v[144:147], v[0:15]
	s_waitcnt lgkmcnt(0)
	v_mfma_f32_32x32x16_bf16 v[0:15], v[100:103], v[148:151], v[0:15]
.Lp3r_halft1:
	s_waitcnt vmcnt(0)
	v_lshlrev_b32_e32 v200, 16, v48
	v_and_b32_e32 v201, s38, v48
	v_lshlrev_b32_e32 v202, 16, v49
	v_and_b32_e32 v203, s38, v49
	v_lshlrev_b32_e32 v204, 16, v50
	v_and_b32_e32 v205, s38, v50
	v_lshlrev_b32_e32 v206, 16, v51
	v_and_b32_e32 v207, s38, v51
	v_lshlrev_b32_e32 v208, 16, v52
	v_and_b32_e32 v209, s38, v52
	v_lshlrev_b32_e32 v210, 16, v53
	v_and_b32_e32 v211, s38, v53
	v_lshlrev_b32_e32 v212, 16, v54
	v_and_b32_e32 v213, s38, v54
	v_lshlrev_b32_e32 v214, 16, v55
	v_and_b32_e32 v215, s38, v55
	s_nop 7
	v_pk_add_f32 v[0:1], v[0:1], v[32:33] op_sel_hi:[1,0]
	v_pk_add_f32 v[2:3], v[2:3], v[32:33] op_sel_hi:[1,0]
	v_pk_add_f32 v[4:5], v[4:5], v[32:33] op_sel_hi:[1,0]
	v_pk_add_f32 v[6:7], v[6:7], v[32:33] op_sel_hi:[1,0]
	v_pk_add_f32 v[8:9], v[8:9], v[32:33] op_sel_hi:[1,0]
	v_pk_add_f32 v[10:11], v[10:11], v[32:33] op_sel_hi:[1,0]
	v_pk_add_f32 v[12:13], v[12:13], v[32:33] op_sel_hi:[1,0]
	v_pk_add_f32 v[14:15], v[14:15], v[32:33] op_sel_hi:[1,0]
	v_pk_mul_f32 v[0:1], v[0:1], v[200:201]
	v_pk_mul_f32 v[2:3], v[2:3], v[202:203]
	v_pk_mul_f32 v[4:5], v[4:5], v[204:205]
	v_pk_mul_f32 v[6:7], v[6:7], v[206:207]
	v_pk_mul_f32 v[8:9], v[8:9], v[208:209]
	v_pk_mul_f32 v[10:11], v[10:11], v[210:211]
	v_pk_mul_f32 v[12:13], v[12:13], v[212:213]
	v_pk_mul_f32 v[14:15], v[14:15], v[214:215]
	v_cvt_pk_bf16_f32 v224, v0, v1
	v_cvt_pk_bf16_f32 v225, v2, v3
	v_cvt_pk_bf16_f32 v226, v4, v5
	v_cvt_pk_bf16_f32 v227, v6, v7
	v_cvt_pk_bf16_f32 v228, v8, v9
	v_cvt_pk_bf16_f32 v229, v10, v11
	v_cvt_pk_bf16_f32 v230, v12, v13
	v_cvt_pk_bf16_f32 v231, v14, v15
	global_store_dwordx2 v116, v[224:225], s[48:49]
	global_store_dwordx2 v116, v[226:227], s[48:49] offset:16
	global_store_dwordx2 v116, v[228:229], s[48:49] offset:32
	global_store_dwordx2 v116, v[230:231], s[48:49] offset:48
	s_add_u32 s48, s48, 0x40000
	s_addc_u32 s49, s49, 0
	s_add_u32 s45, s45, 1
	s_cmp_lt_u32 s45, s18
	s_cbranch_scc0 .Lp3_done
.Lp3r_tail2:
	s_waitcnt vmcnt(5)
	v_lshlrev_b32_e32 v200, 16, v56
	v_and_b32_e32 v201, s38, v56
	v_lshlrev_b32_e32 v202, 16, v57
	v_and_b32_e32 v203, s38, v57
	v_lshlrev_b32_e32 v204, 16, v58
	v_and_b32_e32 v205, s38, v58
	v_lshlrev_b32_e32 v206, 16, v59
	v_and_b32_e32 v207, s38, v59
	s_waitcnt vmcnt(4)
	v_lshlrev_b32_e32 v208, 16, v60
	v_and_b32_e32 v209, s38, v60
	v_lshlrev_b32_e32 v210, 16, v61
	v_and_b32_e32 v211, s38, v61
	v_lshlrev_b32_e32 v212, 16, v62
	v_and_b32_e32 v213, s38, v62
	v_lshlrev_b32_e32 v214, 16, v63
	v_and_b32_e32 v215, s38, v63
	v_pk_add_f32 v[216:217], v[200:201], v[202:203]
	v_pk_add_f32 v[218:219], v[204:205], v[206:207]
	v_pk_add_f32 v[220:221], v[208:209], v[210:211]
	v_pk_add_f32 v[222:223], v[212:213], v[214:215]
	v_pk_add_f32 v[216:217], v[216:217], v[218:219]
	v_pk_add_f32 v[220:221], v[220:221], v[222:223]
	v_pk_add_f32 v[216:217], v[216:217], v[220:221]
	v_add_f32_e32 v216, v216, v217
	s_nop 1
	v_add_f32_dpp v217, v216, v216 quad_perm:[1,0,3,2] row_mask:0xf bank_mask:0xf
	s_nop 1
	v_add_f32_dpp v216, v217, v217 quad_perm:[2,3,0,1] row_mask:0xf bank_mask:0xf
	v_mul_f32_e32 v216, 0xbc800000, v216
	v_pk_add_f32 v[200:201], v[200:201], v[216:217] op_sel_hi:[1,0]
	v_pk_add_f32 v[202:203], v[202:203], v[216:217] op_sel_hi:[1,0]
	v_pk_add_f32 v[204:205], v[204:205], v[216:217] op_sel_hi:[1,0]
	v_pk_add_f32 v[206:207], v[206:207], v[216:217] op_sel_hi:[1,0]
	v_pk_add_f32 v[208:209], v[208:209], v[216:217] op_sel_hi:[1,0]
	v_pk_add_f32 v[210:211], v[210:211], v[216:217] op_sel_hi:[1,0]
	v_pk_add_f32 v[212:213], v[212:213], v[216:217] op_sel_hi:[1,0]
	v_pk_add_f32 v[214:215], v[214:215], v[216:217] op_sel_hi:[1,0]
	v_pk_mul_f32 v[218:219], v[200:201], v[200:201]
	v_pk_mul_f32 v[220:221], v[202:203], v[202:203]
	v_pk_fma_f32 v[218:219], v[204:205], v[204:205], v[218:219]
	v_pk_fma_f32 v[220:221], v[206:207], v[206:207], v[220:221]
	v_pk_fma_f32 v[218:219], v[208:209], v[208:209], v[218:219]
	v_pk_fma_f32 v[220:221], v[210:211], v[210:211], v[220:221]
	v_pk_fma_f32 v[218:219], v[212:213], v[212:213], v[218:219]
	v_pk_fma_f32 v[220:221], v[214:215], v[214:215], v[220:221]
	v_pk_add_f32 v[218:219], v[218:219], v[220:221]
	v_add_f32_e32 v218, v218, v219
	s_nop 1
; #define LAS __attribute__((address_space(3)))
; __global__ void __launch_bounds__(512, 2) mega_fwd(Args a) {
;     ...
;                 const float rstd = rsqrtf(q * (1.0f / 64.0f) + EPS);
; #pragma unroll
;                 for (int e = 0; e < 16; ++e) { const float y = xv[e] * rstd * lgv[e >> 2][e & 3] + lbv[e >> 2][e & 3]; VLT[(16 * qd + e) * VLP + jt] = (bf16_t)(pk2(y, 0.f) & 0xffffu); }
;             }
;             const int un = u + ustep;
;             if (ui + 1 < ucnt) { const bf16_t* vp = Z + ((size_t)(un >> 3) * 128 + jt) * NZ + 1024 + (un & 7) * 64 + 16 * qd; r0 = *(const u32x4*)vp; r1 = *(const u32x4*)(vp + 8);
; #pragma unroll
;                 for (int e4 = 0; e4 < 4; ++e4) { lgv[e4] = *(const f32x4*)(KA->gm_ln_g + (un & 7) * 64 + 16 * qd + 4 * e4); lbv[e4] = *(const f32x4*)(KA->gm_ln_b + (un & 7) * 64 + 16 * qd + 4 * e4); } }
;             const int itok = 32 * iblk + r32;
;             const bf16_t* up = Z + (t0 + itok) * NZ + 512 + h * 64 + 32 * dblk + 4 * hi;
;             u32x2 uu[4];
; #pragma unroll
;             for (int g = 0; g < 4; ++g) uu[g] = *(const u32x2*)(up + 8 * g);
;             const float bsp = KA->b_spatial[h * 128 + itok];
;             bf16x8 wf[8];
;             { const bf16_t* wp = WSP + ((size_t)h * 128 + itok) * 128 + 8 * hi;
; #pragma unroll
;               for (int s = 0; s < 8; ++s) if (s < 4 || iblk >= 2) wf[s] = *(const bf16x8*)(wp + 16 * s); }
;             __syncthreads();
;             {
;                 f32x16 acc;
; #pragma unroll
;                 for (int r = 0; r < 16; ++r) acc[r] = 0.f;
;                 const LAS bf16_t* vl = VLT + (32 * dblk + r32) * VLP + 8 * hi;
; #pragma unroll
;                 for (int s = 0; s < 8; ++s) if (s < 4 || iblk >= 2) {
;                     const bf16x8 vf = *(const LAS bf16x8*)(vl + 16 * s);
;                     acc = __builtin_amdgcn_mfma_f32_32x32x16_bf16(vf, wf[s], acc, 0, 0, 0);
;                 }
;                 bf16_t* op = AO + (t0 + itok) * DM + 512 + h * 64 + 32 * dblk + 4 * hi;
; #pragma unroll
;                 for (int g = 0; g < 4; ++g) {
;                     u32x2 w; w.x = pk2(bf_lo(uu[g].x) * (acc[4 * g] + bsp), bf_hi(uu[g].x) * (acc[4 * g + 1] + bsp)); w.y = pk2(bf_lo(uu[g].y) * (acc[4 * g + 2] + bsp), bf_hi(uu[g].y) * (acc[4 * g + 3] + bsp));
;                     *(u32x2*)(op + 8 * g) = w;
;                 }
	v_add_f32_dpp v219, v218, v218 quad_perm:[1,0,3,2] row_mask:0xf bank_mask:0xf
	s_nop 1
	v_add_f32_dpp v218, v219, v219 quad_perm:[2,3,0,1] row_mask:0xf bank_mask:0xf
	v_fmamk_f32 v218, v218, 0x3c800000, v111
	v_rsq_f32_e32 v218, v218
	s_nop 0
	v_pk_mul_f32 v[200:201], v[200:201], v[218:219] op_sel_hi:[1,0]
	v_pk_mul_f32 v[202:203], v[202:203], v[218:219] op_sel_hi:[1,0]
	v_pk_mul_f32 v[204:205], v[204:205], v[218:219] op_sel_hi:[1,0]
	v_pk_mul_f32 v[206:207], v[206:207], v[218:219] op_sel_hi:[1,0]
	v_pk_mul_f32 v[208:209], v[208:209], v[218:219] op_sel_hi:[1,0]
	v_pk_mul_f32 v[210:211], v[210:211], v[218:219] op_sel_hi:[1,0]
	v_pk_mul_f32 v[212:213], v[212:213], v[218:219] op_sel_hi:[1,0]
	v_pk_mul_f32 v[214:215], v[214:215], v[218:219] op_sel_hi:[1,0]
	v_pk_fma_f32 v[200:201], v[200:201], v[152:153], v[168:169]
	v_pk_fma_f32 v[202:203], v[202:203], v[154:155], v[170:171]
	v_pk_fma_f32 v[204:205], v[204:205], v[156:157], v[172:173]
	v_pk_fma_f32 v[206:207], v[206:207], v[158:159], v[174:175]
	v_pk_fma_f32 v[208:209], v[208:209], v[160:161], v[176:177]
	v_pk_fma_f32 v[210:211], v[210:211], v[162:163], v[178:179]
	v_pk_fma_f32 v[212:213], v[212:213], v[164:165], v[180:181]
	v_pk_fma_f32 v[214:215], v[214:215], v[166:167], v[182:183]
	v_cvt_pk_bf16_f32 v224, v200, v201
	v_cvt_pk_bf16_f32 v225, v202, v203
	v_cvt_pk_bf16_f32 v226, v204, v205
	v_cvt_pk_bf16_f32 v227, v206, v207
	v_cvt_pk_bf16_f32 v228, v208, v209
	v_cvt_pk_bf16_f32 v229, v210, v211
	v_cvt_pk_bf16_f32 v230, v212, v213
	v_cvt_pk_bf16_f32 v231, v214, v215
	ds_write_b16 v117, v224 offset:34816
	ds_write_b16_d16_hi v117, v224 offset:35088
	ds_write_b16 v117, v225 offset:35360
	ds_write_b16_d16_hi v117, v225 offset:35632
	ds_write_b16 v117, v226 offset:35904
	ds_write_b16_d16_hi v117, v226 offset:36176
	ds_write_b16 v117, v227 offset:36448
	ds_write_b16_d16_hi v117, v227 offset:36720
	ds_write_b16 v117, v228 offset:36992
	ds_write_b16_d16_hi v117, v228 offset:37264
	ds_write_b16 v117, v229 offset:37536
	ds_write_b16_d16_hi v117, v229 offset:37808
	ds_write_b16 v117, v230 offset:38080
	ds_write_b16_d16_hi v117, v230 offset:38352
	ds_write_b16 v117, v231 offset:38624
	ds_write_b16_d16_hi v117, v231 offset:38896
	s_waitcnt lgkmcnt(0)
	s_barrier
	ds_read_b128 v[88:91], v118 offset:34816
	ds_read_b128 v[92:95], v118 offset:34848
	ds_read_b128 v[96:99], v118 offset:34880
	ds_read_b128 v[100:103], v118 offset:34912
	s_waitcnt lgkmcnt(3)
	v_mfma_f32_32x32x16_bf16 v[0:15], v[88:91], v[120:123], 0
	s_waitcnt lgkmcnt(2)
	v_mfma_f32_32x32x16_bf16 v[0:15], v[92:95], v[124:127], v[0:15]
	s_waitcnt lgkmcnt(1)
	v_mfma_f32_32x32x16_bf16 v[0:15], v[96:99], v[128:131], v[0:15]
	s_waitcnt lgkmcnt(0)
	v_mfma_f32_32x32x16_bf16 v[0:15], v[100:103], v[132:135], v[0:15]
	s_cmp_lt_u32 s20, 0x100
	s_cbranch_scc1 .Lp3r_halft2
	ds_read_b128 v[88:91], v118 offset:34944
	ds_read_b128 v[92:95], v118 offset:34976
	ds_read_b128 v[96:99], v118 offset:35008
	ds_read_b128 v[100:103], v118 offset:35040
	s_waitcnt lgkmcnt(3)
	v_mfma_f32_32x32x16_bf16 v[0:15], v[88:91], v[136:139], v[0:15]
	s_waitcnt lgkmcnt(2)
	v_mfma_f32_32x32x16_bf16 v[0:15], v[92:95], v[140:143], v[0:15]
	s_waitcnt lgkmcnt(1)
	v_mfma_f32_32x32x16_bf16 v[0:15], v[96:99], v[144:147], v[0:15]
	s_waitcnt lgkmcnt(0)
	v_mfma_f32_32x32x16_bf16 v[0:15], v[100:103], v[148:151], v[0:15]
.Lp3r_halft2:
	s_waitcnt vmcnt(0)
	v_lshlrev_b32_e32 v200, 16, v64
	v_and_b32_e32 v201, s38, v64
	v_lshlrev_b32_e32 v202, 16, v65
	v_and_b32_e32 v203, s38, v65
	v_lshlrev_b32_e32 v204, 16, v66
	v_and_b32_e32 v205, s38, v66
	v_lshlrev_b32_e32 v206, 16, v67
	v_and_b32_e32 v207, s38, v67
	v_lshlrev_b32_e32 v208, 16, v68
	v_and_b32_e32 v209, s38, v68
	v_lshlrev_b32_e32 v210, 16, v69
	v_and_b32_e32 v211, s38, v69
	v_lshlrev_b32_e32 v212, 16, v70
	v_and_b32_e32 v213, s38, v70
	v_lshlrev_b32_e32 v214, 16, v71
	v_and_b32_e32 v215, s38, v71
	s_nop 7
	v_pk_add_f32 v[0:1], v[0:1], v[32:33] op_sel_hi:[1,0]
	v_pk_add_f32 v[2:3], v[2:3], v[32:33] op_sel_hi:[1,0]
	v_pk_add_f32 v[4:5], v[4:5], v[32:33] op_sel_hi:[1,0]
	v_pk_add_f32 v[6:7], v[6:7], v[32:33] op_sel_hi:[1,0]
	v_pk_add_f32 v[8:9], v[8:9], v[32:33] op_sel_hi:[1,0]
	v_pk_add_f32 v[10:11], v[10:11], v[32:33] op_sel_hi:[1,0]
	v_pk_add_f32 v[12:13], v[12:13], v[32:33] op_sel_hi:[1,0]
	v_pk_add_f32 v[14:15], v[14:15], v[32:33] op_sel_hi:[1,0]
	v_pk_mul_f32 v[0:1], v[0:1], v[200:201]
	v_pk_mul_f32 v[2:3], v[2:3], v[202:203]
	v_pk_mul_f32 v[4:5], v[4:5], v[204:205]
	v_pk_mul_f32 v[6:7], v[6:7], v[206:207]
	v_pk_mul_f32 v[8:9], v[8:9], v[208:209]
	v_pk_mul_f32 v[10:11], v[10:11], v[210:211]
	v_pk_mul_f32 v[12:13], v[12:13], v[212:213]
	v_pk_mul_f32 v[14:15], v[14:15], v[214:215]
	v_cvt_pk_bf16_f32 v224, v0, v1
	v_cvt_pk_bf16_f32 v225, v2, v3
	v_cvt_pk_bf16_f32 v226, v4, v5
	v_cvt_pk_bf16_f32 v227, v6, v7
	v_cvt_pk_bf16_f32 v228, v8, v9
	v_cvt_pk_bf16_f32 v229, v10, v11
	v_cvt_pk_bf16_f32 v230, v12, v13
	v_cvt_pk_bf16_f32 v231, v14, v15
	global_store_dwordx2 v116, v[224:225], s[48:49]
	global_store_dwordx2 v116, v[226:227], s[48:49] offset:16
	global_store_dwordx2 v116, v[228:229], s[48:49] offset:32
	global_store_dwordx2 v116, v[230:231], s[48:49] offset:48
	s_add_u32 s48, s48, 0x40000
	s_addc_u32 s49, s49, 0
	s_add_u32 s45, s45, 1
	s_cmp_lt_u32 s45, s18
	s_cbranch_scc0 .Lp3_done
	s_branch .Lp3r_tail0
